# SWA unit epilogues (both layers): the 16x5 serialized ds_bpermute xor steps replaced by DPP adds (xor 1,2,4,8) and permlane16 swap (xor 16); plus the LN wave sums; bit-identical
# speedup vs baseline: 1.0065x; 1.0065x over previous
.LBB0_751:
	v_add_f32_e32 v99, 0, v82
	v_add_f32_e32 v100, 0, v83
	v_mov_b32_e32 v101, v195
	v_mov_b32_e32 v102, v195
	s_nop 0
	v_add_f32_e32 v101, v84, v101
	v_add_f32_e32 v102, v85, v102
	s_nop 0
	v_add_f32_e32 v99, v86, v99
	v_add_f32_e32 v100, v87, v100
	v_cvt_pk_bf16_f32 v82, v82, v83
	v_cvt_pk_bf16_f32 v83, v84, v85
	v_cvt_pk_bf16_f32 v84, v86, v87
	v_cvt_pk_bf16_f32 v85, v88, v89
	s_nop 0
	v_permlane32_swap_b32_e32 v82, v84
	v_permlane32_swap_b32_e32 v83, v85
	v_add_f32_e32 v86, v88, v101
	v_add_f32_e32 v87, v89, v102
	s_nop 0
	v_add_f32_e32 v88, v90, v99
	v_add_f32_e32 v89, v91, v100
	s_nop 0
	v_add_f32_e32 v99, v92, v86
	v_add_f32_e32 v100, v93, v87
	s_nop 0
	v_add_f32_e32 v101, v94, v88
	v_add_f32_e32 v102, v95, v89
	v_cvt_pk_bf16_f32 v86, v90, v91
	v_cvt_pk_bf16_f32 v87, v92, v93
	v_cvt_pk_bf16_f32 v88, v94, v95
	v_cvt_pk_bf16_f32 v89, v96, v97
	s_nop 0
	v_permlane32_swap_b32_e32 v86, v88
	v_permlane32_swap_b32_e32 v87, v89
	v_add_f32_e32 v90, v96, v99
	v_add_f32_e32 v91, v97, v100
	s_nop 0
	v_add_f32_e32 v92, v66, v101
	v_add_f32_e32 v93, v67, v102
	s_nop 0
	v_add_f32_e32 v94, v68, v90
	v_add_f32_e32 v95, v69, v91
	s_nop 0
	v_add_f32_e32 v96, v70, v92
	v_add_f32_e32 v97, v71, v93
	v_cvt_pk_bf16_f32 v90, v66, v67
	v_cvt_pk_bf16_f32 v91, v68, v69
	v_cvt_pk_bf16_f32 v92, v70, v71
	v_cvt_pk_bf16_f32 v93, v72, v73
	s_nop 0
	v_permlane32_swap_b32_e32 v90, v92
	v_permlane32_swap_b32_e32 v91, v93
	v_add_f32_e32 v66, v72, v94
	v_add_f32_e32 v67, v73, v95
	s_nop 0
	v_add_f32_e32 v68, v74, v96
	v_add_f32_e32 v69, v75, v97
	s_nop 0
	v_add_f32_e32 v66, v76, v66
	v_add_f32_e32 v67, v77, v67
	s_nop 0
	v_add_f32_e32 v72, v78, v68
	v_add_f32_e32 v73, v79, v69
	v_cvt_pk_bf16_f32 v68, v74, v75
	v_cvt_pk_bf16_f32 v69, v76, v77
	v_cvt_pk_bf16_f32 v70, v78, v79
	v_cvt_pk_bf16_f32 v71, v80, v81
	s_nop 0
	v_permlane32_swap_b32_e32 v68, v70
	v_permlane32_swap_b32_e32 v69, v71
	v_add_f32_e32 v66, v80, v66
	v_add_f32_e32 v67, v81, v67
	s_nop 0
	v_add_f32_e32 v72, v72, v73
	v_add_f32_e32 v66, v66, v67
	v_add_u32_e32 v99, s10, v211
	v_add_f32_e32 v66, v72, v66
	ds_read_b64_tr_b16 v[72:73], v99
	ds_read_b64_tr_b16 v[74:75], v99 offset:2048
	ds_read_b64_tr_b16 v[76:77], v99 offset:512
	ds_read_b64_tr_b16 v[94:95], v99 offset:1024
	ds_read_b64_tr_b16 v[78:79], v99 offset:2560
	ds_read_b64_tr_b16 v[96:97], v99 offset:3072
	s_waitcnt lgkmcnt(4)
	v_mfma_f32_32x32x16_bf16 v[2:17], v[82:85], v[72:75], v[2:17]
	v_mov_b32_e32 v67, v66
	s_nop 1
	v_permlane32_swap_b32_e32 v66, v67
	s_waitcnt lgkmcnt(1)
	v_mfma_f32_32x32x16_bf16 v[50:65], v[82:85], v[76:79], v[50:65]
	ds_read_b64_tr_b16 v[72:73], v99 offset:1536
	ds_read_b64_tr_b16 v[74:75], v99 offset:3584
	s_waitcnt lgkmcnt(2)
	v_mfma_f32_32x32x16_bf16 v[34:49], v[82:85], v[94:97], v[34:49]
	ds_read_b64_tr_b16 v[76:77], v99 offset:4096
	ds_read_b64_tr_b16 v[78:79], v99 offset:6144
	s_waitcnt lgkmcnt(2)
	v_mfma_f32_32x32x16_bf16 v[18:33], v[82:85], v[72:75], v[18:33]
	ds_read_b64_tr_b16 v[94:95], v99 offset:4608
	ds_read_b64_tr_b16 v[96:97], v99 offset:6656
	s_waitcnt lgkmcnt(2)
	v_mfma_f32_32x32x16_bf16 v[2:17], v[86:89], v[76:79], v[2:17]
	ds_read_b64_tr_b16 v[72:73], v99 offset:5120
	ds_read_b64_tr_b16 v[74:75], v99 offset:7168
	s_waitcnt lgkmcnt(2)
	v_mfma_f32_32x32x16_bf16 v[50:65], v[86:89], v[94:97], v[50:65]
	ds_read_b64_tr_b16 v[76:77], v99 offset:5632
	ds_read_b64_tr_b16 v[78:79], v99 offset:7680
	s_waitcnt lgkmcnt(2)
	v_mfma_f32_32x32x16_bf16 v[34:49], v[86:89], v[72:75], v[34:49]
	ds_read_b64_tr_b16 v[80:81], v99 offset:8192
	ds_read_b64_tr_b16 v[82:83], v99 offset:10240
	s_waitcnt lgkmcnt(2)
	v_mfma_f32_32x32x16_bf16 v[18:33], v[86:89], v[76:79], v[18:33]
	ds_read_b64_tr_b16 v[72:73], v99 offset:8704
	ds_read_b64_tr_b16 v[74:75], v99 offset:10752
	s_waitcnt lgkmcnt(2)
	v_mfma_f32_32x32x16_bf16 v[2:17], v[90:93], v[80:83], v[2:17]
	ds_read_b64_tr_b16 v[76:77], v99 offset:9216
	ds_read_b64_tr_b16 v[78:79], v99 offset:11264
	s_waitcnt lgkmcnt(2)
	v_mfma_f32_32x32x16_bf16 v[50:65], v[90:93], v[72:75], v[50:65]
	ds_read_b64_tr_b16 v[80:81], v99 offset:9728
	ds_read_b64_tr_b16 v[82:83], v99 offset:11776
	s_waitcnt lgkmcnt(2)
	v_mfma_f32_32x32x16_bf16 v[34:49], v[90:93], v[76:79], v[34:49]
	ds_read_b64_tr_b16 v[72:73], v99 offset:12288
	ds_read_b64_tr_b16 v[74:75], v99 offset:14336
	s_waitcnt lgkmcnt(2)
	v_mfma_f32_32x32x16_bf16 v[18:33], v[90:93], v[80:83], v[18:33]
	ds_read_b64_tr_b16 v[76:77], v99 offset:12800
	ds_read_b64_tr_b16 v[78:79], v99 offset:14848
	s_waitcnt lgkmcnt(2)
	v_mfma_f32_32x32x16_bf16 v[2:17], v[68:71], v[72:75], v[2:17]
	ds_read_b64_tr_b16 v[80:81], v99 offset:13312
	ds_read_b64_tr_b16 v[82:83], v99 offset:15360
	s_waitcnt lgkmcnt(2)
	v_mfma_f32_32x32x16_bf16 v[50:65], v[68:71], v[76:79], v[50:65]
	ds_read_b64_tr_b16 v[72:73], v99 offset:13824
	ds_read_b64_tr_b16 v[74:75], v99 offset:15872
	s_waitcnt lgkmcnt(2)
	v_mfma_f32_32x32x16_bf16 v[34:49], v[68:71], v[80:83], v[34:49]
	s_waitcnt lgkmcnt(0)
	v_mfma_f32_32x32x16_bf16 v[18:33], v[68:71], v[72:75], v[18:33]
	v_cmp_gt_u32_e32 vcc, 32, v194
	s_and_saveexec_b64 s[4:5], vcc
	v_add_f32_e32 v68, v130, v131
	v_fmac_f32_e32 v68, v197, v212
	v_add_f32_e32 v66, v66, v67
	v_fmac_f32_e32 v66, v68, v98
	ds_write_b32 v213, v66
	s_or_b64 exec, exec, s[4:5]
	s_waitcnt lgkmcnt(0)
	ds_read_b32 v66, v208
	s_lshl_b32 s4, s42, 12
	s_add_u32 s6, s72, s4
	s_addc_u32 s7, s73, 0
	s_add_u32 s4, s6, s20
	s_waitcnt lgkmcnt(0)
	v_rcp_f32_e32 v66, v66
	s_addc_u32 s5, s7, s21
	s_mul_hi_i32 s10, s42, 0xfffff040
	s_mulk_i32 s42, 0xf040
	v_mul_f32_e32 v68, v2, v66
	v_mul_f32_e32 v69, v50, v66
	v_and_b32_e32 v2, 64, v206
	v_mul_f32_e32 v50, v69, v69
	v_add_u32_e32 v70, 64, v2
	v_xor_b32_e32 v2, 1, v206
	v_fmac_f32_e32 v50, v68, v68
	v_mul_f32_e32 v71, v34, v66
	v_cmp_lt_i32_e32 vcc, v2, v70
	v_fmac_f32_e32 v50, v71, v71
	v_mul_f32_e32 v74, v18, v66
	v_cndmask_b32_e32 v2, v206, v2, vcc
	v_fmac_f32_e32 v50, v74, v74
	v_lshlrev_b32_e32 v2, 2, v2
	s_add_u32 s6, s6, s42
	s_addc_u32 s7, s7, s10
	s_add_u32 s6, s6, s18
	s_addc_u32 s7, s7, s19
	s_waitcnt lgkmcnt(0)
	v_add_f32_dpp v34, v50, v50 quad_perm:[1,0,3,2] row_mask:0xf bank_mask:0xf
	v_xor_b32_e32 v18, 2, v206
	v_cmp_lt_i32_e32 vcc, v18, v70
	v_ashrrev_i32_e32 v197, 31, v196
	s_add_u32 s18, s6, 0xf00020
	v_cndmask_b32_e32 v18, v206, v18, vcc
	v_lshlrev_b32_e32 v18, 2, v18
	v_lshlrev_b64 v[66:67], 12, v[196:197]
	s_addc_u32 s19, s7, 0
	v_lshl_add_u64 v[66:67], s[4:5], 0, v[66:67]
	v_lshlrev_b32_e32 v194, 1, v209
	s_waitcnt lgkmcnt(0)
	v_add_f32_dpp v50, v34, v34 quad_perm:[2,3,0,1] row_mask:0xf bank_mask:0xf
	v_xor_b32_e32 v34, 4, v206
	v_cmp_lt_i32_e32 vcc, v34, v70
	v_lshl_add_u64 v[66:67], v[66:67], 0, v[194:195]
	v_lshl_add_u64 v[66:67], v[66:67], 0, s[16:17]
	v_cndmask_b32_e32 v34, v206, v34, vcc
	v_lshlrev_b32_e32 v34, 2, v34
	v_lshlrev_b32_e32 v194, 14, v210
	v_lshl_add_u64 v[72:73], v[66:67], 0, v[194:195]
	v_cvt_pk_bf16_f32 v68, v68, v68
	global_store_short v[72:73], v68, off
	s_waitcnt lgkmcnt(0)
	v_add_f32_dpp v75, v50, v50 row_half_mirror row_mask:0xf bank_mask:0xf
	v_xor_b32_e32 v50, 8, v206
	v_cmp_lt_i32_e64 s[6:7], v50, v70
	v_cvt_pk_bf16_f32 v68, v69, v69
	global_store_short v[72:73], v68, off offset:64
	v_xor_b32_e32 v68, 16, v206
	v_cndmask_b32_e64 v50, v206, v50, s[6:7]
	v_lshlrev_b32_e32 v50, 2, v50
	v_cmp_lt_i32_e64 s[6:7], v68, v70
	v_cmp_eq_u32_e32 vcc, 0, v209
	v_cvt_pk_bf16_f32 v71, v71, v71
	global_store_short v[72:73], v71, off offset:128
	v_cndmask_b32_e64 v68, v206, v68, s[6:7]
	s_waitcnt lgkmcnt(0)
	v_add_f32_dpp v69, v75, v75 row_mirror row_mask:0xf bank_mask:0xf
	v_lshlrev_b32_e32 v68, 2, v68
	v_mov_b32_e32 v70, v69
	s_nop 1
	v_permlane16_swap_b32_e32 v69, v70
	v_cvt_pk_bf16_f32 v71, v74, v74
	global_store_short v[72:73], v71, off offset:192
	s_and_saveexec_b64 s[4:5], vcc
	s_cbranch_execz .LBB0_755
	s_waitcnt lgkmcnt(0)
	v_add_f32_e32 v69, v69, v70
	v_or_b32_e32 v70, v207, v196
	v_ashrrev_i32_e32 v71, 31, v70
	v_lshlrev_b64 v[70:71], 6, v[70:71]
	v_lshl_add_u64 v[70:71], s[18:19], 0, v[70:71]
	global_store_dword v[70:71], v69, off
.LBB0_755:
	s_or_b64 exec, exec, s[4:5]
	ds_read_b32 v69, v208 offset:4
	s_waitcnt lgkmcnt(0)
	v_rcp_f32_e32 v69, v69
	s_nop 0
	v_mul_f32_e32 v51, v51, v69
	v_mul_f32_e32 v72, v3, v69
	v_mul_f32_e32 v3, v51, v51
	v_mul_f32_e32 v73, v35, v69
	v_fmac_f32_e32 v3, v72, v72
	v_fmac_f32_e32 v3, v73, v73
	v_mul_f32_e32 v69, v19, v69
	v_fmac_f32_e32 v3, v69, v69
	v_cvt_pk_bf16_f32 v72, v72, v72
	s_waitcnt lgkmcnt(0)
	v_add_f32_dpp v3, v3, v3 quad_perm:[1,0,3,2] row_mask:0xf bank_mask:0xf
	s_waitcnt lgkmcnt(0)
	s_nop 1
	v_add_f32_dpp v19, v3, v3 quad_perm:[2,3,0,1] row_mask:0xf bank_mask:0xf
	v_or_b32_e32 v3, 1, v207
	v_lshlrev_b32_e32 v194, 12, v3
	v_lshl_add_u64 v[70:71], v[66:67], 0, v[194:195]
	global_store_short v[70:71], v72, off
	s_waitcnt lgkmcnt(0)
	v_add_f32_dpp v19, v19, v19 row_half_mirror row_mask:0xf bank_mask:0xf
	v_cvt_pk_bf16_f32 v51, v51, v51
	global_store_short v[70:71], v51, off offset:64
	v_cvt_pk_bf16_f32 v51, v73, v73
	global_store_short v[70:71], v51, off offset:128
	s_waitcnt lgkmcnt(0)
	v_add_f32_dpp v19, v19, v19 row_mirror row_mask:0xf bank_mask:0xf
	v_mov_b32_e32 v35, v19
	s_nop 1
	v_permlane16_swap_b32_e32 v19, v35
	v_cvt_pk_bf16_f32 v51, v69, v69
	global_store_short v[70:71], v51, off offset:192
	s_and_saveexec_b64 s[4:5], vcc
	s_cbranch_execz .LBB0_757
	v_or_b32_e32 v70, v3, v196
	v_ashrrev_i32_e32 v71, 31, v70
	v_lshlrev_b64 v[70:71], 6, v[70:71]
	s_waitcnt lgkmcnt(0)
	v_add_f32_e32 v19, v19, v35
	v_lshl_add_u64 v[70:71], s[18:19], 0, v[70:71]
	global_store_dword v[70:71], v19, off
.LBB0_757:
	s_or_b64 exec, exec, s[4:5]
	ds_read_b32 v3, v208 offset:8
	s_waitcnt lgkmcnt(0)
	v_rcp_f32_e32 v3, v3
	s_nop 0
	v_mul_f32_e32 v19, v52, v3
	v_mul_f32_e32 v4, v4, v3
	v_mul_f32_e32 v35, v36, v3
	v_mul_f32_e32 v36, v19, v19
	v_fmac_f32_e32 v36, v4, v4
	v_fmac_f32_e32 v36, v35, v35
	v_mul_f32_e32 v20, v20, v3
	v_fmac_f32_e32 v36, v20, v20
	v_cvt_pk_bf16_f32 v4, v4, v4
	s_waitcnt lgkmcnt(0)
	v_add_f32_dpp v3, v36, v36 quad_perm:[1,0,3,2] row_mask:0xf bank_mask:0xf
	s_waitcnt lgkmcnt(0)
	s_nop 1
	v_add_f32_dpp v36, v3, v3 quad_perm:[2,3,0,1] row_mask:0xf bank_mask:0xf
	v_or_b32_e32 v3, 2, v207
	v_lshlrev_b32_e32 v194, 12, v3
	v_lshl_add_u64 v[70:71], v[66:67], 0, v[194:195]
	global_store_short v[70:71], v4, off
	s_waitcnt lgkmcnt(0)
	v_add_f32_dpp v36, v36, v36 row_half_mirror row_mask:0xf bank_mask:0xf
	v_cvt_pk_bf16_f32 v4, v19, v19
	global_store_short v[70:71], v4, off offset:64
	v_cvt_pk_bf16_f32 v35, v35, v35
	global_store_short v[70:71], v35, off offset:128
	s_waitcnt lgkmcnt(0)
	v_add_f32_dpp v4, v36, v36 row_mirror row_mask:0xf bank_mask:0xf
	v_mov_b32_e32 v19, v4
	s_nop 1
	v_permlane16_swap_b32_e32 v4, v19
	v_cvt_pk_bf16_f32 v20, v20, v20
	global_store_short v[70:71], v20, off offset:192
	s_and_saveexec_b64 s[4:5], vcc
	s_cbranch_execz .LBB0_759
	v_or_b32_e32 v70, v3, v196
	v_ashrrev_i32_e32 v71, 31, v70
	v_lshlrev_b64 v[70:71], 6, v[70:71]
	s_waitcnt lgkmcnt(0)
	v_add_f32_e32 v4, v4, v19
	v_lshl_add_u64 v[70:71], s[18:19], 0, v[70:71]
	global_store_dword v[70:71], v4, off
.LBB0_759:
	s_or_b64 exec, exec, s[4:5]
	ds_read_b32 v3, v208 offset:12
	s_waitcnt lgkmcnt(0)
	v_rcp_f32_e32 v3, v3
	s_nop 0
	v_mul_f32_e32 v4, v5, v3
	v_mul_f32_e32 v5, v53, v3
	v_mul_f32_e32 v20, v5, v5
	v_mul_f32_e32 v19, v37, v3
	v_fmac_f32_e32 v20, v4, v4
	v_fmac_f32_e32 v20, v19, v19
	v_mul_f32_e32 v35, v21, v3
	v_fmac_f32_e32 v20, v35, v35
	v_cvt_pk_bf16_f32 v4, v4, v4
	s_waitcnt lgkmcnt(0)
	v_add_f32_dpp v3, v20, v20 quad_perm:[1,0,3,2] row_mask:0xf bank_mask:0xf
	s_waitcnt lgkmcnt(0)
	s_nop 1
	v_add_f32_dpp v36, v3, v3 quad_perm:[2,3,0,1] row_mask:0xf bank_mask:0xf
	v_or_b32_e32 v3, 3, v207
	v_lshlrev_b32_e32 v194, 12, v3
	v_lshl_add_u64 v[20:21], v[66:67], 0, v[194:195]
	global_store_short v[20:21], v4, off
	s_waitcnt lgkmcnt(0)
	v_add_f32_dpp v36, v36, v36 row_half_mirror row_mask:0xf bank_mask:0xf
	v_cvt_pk_bf16_f32 v4, v5, v5
	global_store_short v[20:21], v4, off offset:64
	v_cvt_pk_bf16_f32 v19, v19, v19
	global_store_short v[20:21], v19, off offset:128
	s_waitcnt lgkmcnt(0)
	v_add_f32_dpp v4, v36, v36 row_mirror row_mask:0xf bank_mask:0xf
	v_mov_b32_e32 v5, v4
	s_nop 1
	v_permlane16_swap_b32_e32 v4, v5
	v_cvt_pk_bf16_f32 v19, v35, v35
	global_store_short v[20:21], v19, off offset:192
	s_and_saveexec_b64 s[4:5], vcc
	s_cbranch_execz .LBB0_761
	s_waitcnt lgkmcnt(0)
	v_add_f32_e32 v19, v4, v5
	v_or_b32_e32 v4, v3, v196
	v_ashrrev_i32_e32 v5, 31, v4
	v_lshlrev_b64 v[4:5], 6, v[4:5]
	v_lshl_add_u64 v[4:5], s[18:19], 0, v[4:5]
	global_store_dword v[4:5], v19, off
.LBB0_761:
	s_or_b64 exec, exec, s[4:5]
	ds_read_b32 v3, v208 offset:32
	s_waitcnt lgkmcnt(0)
	v_rcp_f32_e32 v3, v3
	s_nop 0
	v_mul_f32_e32 v5, v54, v3
	v_mul_f32_e32 v4, v6, v3
	v_mul_f32_e32 v19, v5, v5
	v_mul_f32_e32 v6, v38, v3
	v_fmac_f32_e32 v19, v4, v4
	v_fmac_f32_e32 v19, v6, v6
	v_mul_f32_e32 v22, v22, v3
	v_fmac_f32_e32 v19, v22, v22
	v_cvt_pk_bf16_f32 v4, v4, v4
	s_waitcnt lgkmcnt(0)
	v_add_f32_dpp v3, v19, v19 quad_perm:[1,0,3,2] row_mask:0xf bank_mask:0xf
	s_waitcnt lgkmcnt(0)
	s_nop 1
	v_add_f32_dpp v19, v3, v3 quad_perm:[2,3,0,1] row_mask:0xf bank_mask:0xf
	v_or_b32_e32 v3, 8, v207
	v_lshlrev_b32_e32 v194, 12, v3
	v_lshl_add_u64 v[20:21], v[66:67], 0, v[194:195]
	global_store_short v[20:21], v4, off
	s_waitcnt lgkmcnt(0)
	v_add_f32_dpp v19, v19, v19 row_half_mirror row_mask:0xf bank_mask:0xf
	v_cvt_pk_bf16_f32 v4, v5, v5
	global_store_short v[20:21], v4, off offset:64
	v_cvt_pk_bf16_f32 v6, v6, v6
	global_store_short v[20:21], v6, off offset:128
	s_waitcnt lgkmcnt(0)
	v_add_f32_dpp v4, v19, v19 row_mirror row_mask:0xf bank_mask:0xf
	v_mov_b32_e32 v5, v4
	s_nop 1
	v_permlane16_swap_b32_e32 v4, v5
	v_cvt_pk_bf16_f32 v6, v22, v22
	global_store_short v[20:21], v6, off offset:192
	s_and_saveexec_b64 s[4:5], vcc
	s_cbranch_execz .LBB0_763
	s_waitcnt lgkmcnt(0)
	v_add_f32_e32 v6, v4, v5
	v_or_b32_e32 v4, v3, v196
	v_ashrrev_i32_e32 v5, 31, v4
	v_lshlrev_b64 v[4:5], 6, v[4:5]
	v_lshl_add_u64 v[4:5], s[18:19], 0, v[4:5]
	global_store_dword v[4:5], v6, off
.LBB0_763:
	s_or_b64 exec, exec, s[4:5]
	ds_read_b32 v3, v208 offset:36
	s_waitcnt lgkmcnt(0)
	v_rcp_f32_e32 v3, v3
	s_nop 0
	v_mul_f32_e32 v5, v55, v3
	v_mul_f32_e32 v4, v7, v3
	v_mul_f32_e32 v6, v5, v5
	v_mul_f32_e32 v19, v39, v3
	v_fmac_f32_e32 v6, v4, v4
	v_fmac_f32_e32 v6, v19, v19
	v_mul_f32_e32 v20, v23, v3
	v_fmac_f32_e32 v6, v20, v20
	v_cvt_pk_bf16_f32 v4, v4, v4
	s_waitcnt lgkmcnt(0)
	v_add_f32_dpp v3, v6, v6 quad_perm:[1,0,3,2] row_mask:0xf bank_mask:0xf
	s_waitcnt lgkmcnt(0)
	s_nop 1
	v_add_f32_dpp v21, v3, v3 quad_perm:[2,3,0,1] row_mask:0xf bank_mask:0xf
	v_or_b32_e32 v3, 9, v207
	v_lshlrev_b32_e32 v194, 12, v3
	v_lshl_add_u64 v[6:7], v[66:67], 0, v[194:195]
	global_store_short v[6:7], v4, off
	s_waitcnt lgkmcnt(0)
	v_add_f32_dpp v21, v21, v21 row_half_mirror row_mask:0xf bank_mask:0xf
	v_cvt_pk_bf16_f32 v4, v5, v5
	global_store_short v[6:7], v4, off offset:64
	v_cvt_pk_bf16_f32 v19, v19, v19
	global_store_short v[6:7], v19, off offset:128
	s_waitcnt lgkmcnt(0)
	v_add_f32_dpp v4, v21, v21 row_mirror row_mask:0xf bank_mask:0xf
	v_mov_b32_e32 v5, v4
	s_nop 1
	v_permlane16_swap_b32_e32 v4, v5
	v_cvt_pk_bf16_f32 v19, v20, v20
	global_store_short v[6:7], v19, off offset:192
	s_and_saveexec_b64 s[4:5], vcc
	s_cbranch_execz .LBB0_765
	s_waitcnt lgkmcnt(0)
	v_add_f32_e32 v6, v4, v5
	v_or_b32_e32 v4, v3, v196
	v_ashrrev_i32_e32 v5, 31, v4
	v_lshlrev_b64 v[4:5], 6, v[4:5]
	v_lshl_add_u64 v[4:5], s[18:19], 0, v[4:5]
	global_store_dword v[4:5], v6, off
.LBB0_765:
	s_or_b64 exec, exec, s[4:5]
	ds_read_b32 v3, v208 offset:40
	s_waitcnt lgkmcnt(0)
	v_rcp_f32_e32 v3, v3
	s_nop 0
	v_mul_f32_e32 v5, v56, v3
	v_mul_f32_e32 v4, v8, v3
	v_mul_f32_e32 v6, v5, v5
	v_mul_f32_e32 v8, v40, v3
	v_fmac_f32_e32 v6, v4, v4
	v_fmac_f32_e32 v6, v8, v8
	v_mul_f32_e32 v19, v24, v3
	v_fmac_f32_e32 v6, v19, v19
	v_cvt_pk_bf16_f32 v4, v4, v4
	s_waitcnt lgkmcnt(0)
	v_add_f32_dpp v3, v6, v6 quad_perm:[1,0,3,2] row_mask:0xf bank_mask:0xf
	s_waitcnt lgkmcnt(0)
	s_nop 1
	v_add_f32_dpp v20, v3, v3 quad_perm:[2,3,0,1] row_mask:0xf bank_mask:0xf
	v_or_b32_e32 v3, 10, v207
	v_lshlrev_b32_e32 v194, 12, v3
	v_lshl_add_u64 v[6:7], v[66:67], 0, v[194:195]
	global_store_short v[6:7], v4, off
	s_waitcnt lgkmcnt(0)
	v_add_f32_dpp v20, v20, v20 row_half_mirror row_mask:0xf bank_mask:0xf
	v_cvt_pk_bf16_f32 v4, v5, v5
	global_store_short v[6:7], v4, off offset:64
	v_cvt_pk_bf16_f32 v8, v8, v8
	global_store_short v[6:7], v8, off offset:128
	s_waitcnt lgkmcnt(0)
	v_add_f32_dpp v4, v20, v20 row_mirror row_mask:0xf bank_mask:0xf
	v_mov_b32_e32 v5, v4
	s_nop 1
	v_permlane16_swap_b32_e32 v4, v5
	v_cvt_pk_bf16_f32 v8, v19, v19
	global_store_short v[6:7], v8, off offset:192
	s_and_saveexec_b64 s[4:5], vcc
	s_cbranch_execz .LBB0_767
	s_waitcnt lgkmcnt(0)
	v_add_f32_e32 v6, v4, v5
	v_or_b32_e32 v4, v3, v196
	v_ashrrev_i32_e32 v5, 31, v4
	v_lshlrev_b64 v[4:5], 6, v[4:5]
	v_lshl_add_u64 v[4:5], s[18:19], 0, v[4:5]
	global_store_dword v[4:5], v6, off
.LBB0_767:
	s_or_b64 exec, exec, s[4:5]
	ds_read_b32 v3, v208 offset:44
	s_waitcnt lgkmcnt(0)
	v_rcp_f32_e32 v3, v3
	s_nop 0
	v_mul_f32_e32 v5, v57, v3
	v_mul_f32_e32 v4, v9, v3
	v_mul_f32_e32 v6, v5, v5
	v_mul_f32_e32 v8, v41, v3
	v_fmac_f32_e32 v6, v4, v4
	v_fmac_f32_e32 v6, v8, v8
	v_mul_f32_e32 v9, v25, v3
	v_fmac_f32_e32 v6, v9, v9
	v_cvt_pk_bf16_f32 v4, v4, v4
	s_waitcnt lgkmcnt(0)
	v_add_f32_dpp v3, v6, v6 quad_perm:[1,0,3,2] row_mask:0xf bank_mask:0xf
	s_waitcnt lgkmcnt(0)
	s_nop 1
	v_add_f32_dpp v19, v3, v3 quad_perm:[2,3,0,1] row_mask:0xf bank_mask:0xf
	v_or_b32_e32 v3, 11, v207
	v_lshlrev_b32_e32 v194, 12, v3
	v_lshl_add_u64 v[6:7], v[66:67], 0, v[194:195]
	global_store_short v[6:7], v4, off
	s_waitcnt lgkmcnt(0)
	v_add_f32_dpp v19, v19, v19 row_half_mirror row_mask:0xf bank_mask:0xf
	v_cvt_pk_bf16_f32 v4, v5, v5
	global_store_short v[6:7], v4, off offset:64
	v_cvt_pk_bf16_f32 v8, v8, v8
	global_store_short v[6:7], v8, off offset:128
	s_waitcnt lgkmcnt(0)
	v_add_f32_dpp v4, v19, v19 row_mirror row_mask:0xf bank_mask:0xf
	v_mov_b32_e32 v5, v4
	s_nop 1
	v_permlane16_swap_b32_e32 v4, v5
	v_cvt_pk_bf16_f32 v8, v9, v9
	global_store_short v[6:7], v8, off offset:192
	s_and_saveexec_b64 s[4:5], vcc
	s_cbranch_execz .LBB0_769
	s_waitcnt lgkmcnt(0)
	v_add_f32_e32 v6, v4, v5
	v_or_b32_e32 v4, v3, v196
	v_ashrrev_i32_e32 v5, 31, v4
	v_lshlrev_b64 v[4:5], 6, v[4:5]
	v_lshl_add_u64 v[4:5], s[18:19], 0, v[4:5]
	global_store_dword v[4:5], v6, off
.LBB0_769:
	s_or_b64 exec, exec, s[4:5]
	ds_read_b32 v3, v208 offset:64
	s_waitcnt lgkmcnt(0)
	v_rcp_f32_e32 v3, v3
	s_nop 0
	v_mul_f32_e32 v5, v58, v3
	v_mul_f32_e32 v4, v10, v3
	v_mul_f32_e32 v6, v5, v5
	v_mul_f32_e32 v8, v42, v3
	v_fmac_f32_e32 v6, v4, v4
	v_fmac_f32_e32 v6, v8, v8
	v_mul_f32_e32 v9, v26, v3
	v_fmac_f32_e32 v6, v9, v9
	v_cvt_pk_bf16_f32 v4, v4, v4
	s_waitcnt lgkmcnt(0)
	v_add_f32_dpp v3, v6, v6 quad_perm:[1,0,3,2] row_mask:0xf bank_mask:0xf
	s_waitcnt lgkmcnt(0)
	s_nop 1
	v_add_f32_dpp v10, v3, v3 quad_perm:[2,3,0,1] row_mask:0xf bank_mask:0xf
	v_or_b32_e32 v3, 16, v207
	v_lshlrev_b32_e32 v194, 12, v3
	v_lshl_add_u64 v[6:7], v[66:67], 0, v[194:195]
	global_store_short v[6:7], v4, off
	s_waitcnt lgkmcnt(0)
	v_add_f32_dpp v10, v10, v10 row_half_mirror row_mask:0xf bank_mask:0xf
	v_cvt_pk_bf16_f32 v4, v5, v5
	global_store_short v[6:7], v4, off offset:64
	v_cvt_pk_bf16_f32 v8, v8, v8
	global_store_short v[6:7], v8, off offset:128
	s_waitcnt lgkmcnt(0)
	v_add_f32_dpp v4, v10, v10 row_mirror row_mask:0xf bank_mask:0xf
	v_mov_b32_e32 v5, v4
	s_nop 1
	v_permlane16_swap_b32_e32 v4, v5
	v_cvt_pk_bf16_f32 v8, v9, v9
	global_store_short v[6:7], v8, off offset:192
	s_and_saveexec_b64 s[4:5], vcc
	s_cbranch_execz .LBB0_771
	s_waitcnt lgkmcnt(0)
	v_add_f32_e32 v6, v4, v5
	v_or_b32_e32 v4, v3, v196
	v_ashrrev_i32_e32 v5, 31, v4
	v_lshlrev_b64 v[4:5], 6, v[4:5]
	v_lshl_add_u64 v[4:5], s[18:19], 0, v[4:5]
	global_store_dword v[4:5], v6, off
.LBB0_771:
	s_or_b64 exec, exec, s[4:5]
	ds_read_b32 v3, v208 offset:68
	s_waitcnt lgkmcnt(0)
	v_rcp_f32_e32 v3, v3
	s_nop 0
	v_mul_f32_e32 v5, v59, v3
	v_mul_f32_e32 v4, v11, v3
	v_mul_f32_e32 v6, v5, v5
	v_mul_f32_e32 v8, v43, v3
	v_fmac_f32_e32 v6, v4, v4
	v_fmac_f32_e32 v6, v8, v8
	v_mul_f32_e32 v9, v27, v3
	v_fmac_f32_e32 v6, v9, v9
	v_cvt_pk_bf16_f32 v4, v4, v4
	s_waitcnt lgkmcnt(0)
	v_add_f32_dpp v3, v6, v6 quad_perm:[1,0,3,2] row_mask:0xf bank_mask:0xf
	s_waitcnt lgkmcnt(0)
	s_nop 1
	v_add_f32_dpp v10, v3, v3 quad_perm:[2,3,0,1] row_mask:0xf bank_mask:0xf
	v_or_b32_e32 v3, 17, v207
	v_lshlrev_b32_e32 v194, 12, v3
	v_lshl_add_u64 v[6:7], v[66:67], 0, v[194:195]
	global_store_short v[6:7], v4, off
	s_waitcnt lgkmcnt(0)
	v_add_f32_dpp v10, v10, v10 row_half_mirror row_mask:0xf bank_mask:0xf
	v_cvt_pk_bf16_f32 v4, v5, v5
	global_store_short v[6:7], v4, off offset:64
	v_cvt_pk_bf16_f32 v8, v8, v8
	global_store_short v[6:7], v8, off offset:128
	s_waitcnt lgkmcnt(0)
	v_add_f32_dpp v4, v10, v10 row_mirror row_mask:0xf bank_mask:0xf
	v_mov_b32_e32 v5, v4
	s_nop 1
	v_permlane16_swap_b32_e32 v4, v5
	v_cvt_pk_bf16_f32 v8, v9, v9
	global_store_short v[6:7], v8, off offset:192
	s_and_saveexec_b64 s[4:5], vcc
	s_cbranch_execz .LBB0_773
	s_waitcnt lgkmcnt(0)
	v_add_f32_e32 v6, v4, v5
	v_or_b32_e32 v4, v3, v196
	v_ashrrev_i32_e32 v5, 31, v4
	v_lshlrev_b64 v[4:5], 6, v[4:5]
	v_lshl_add_u64 v[4:5], s[18:19], 0, v[4:5]
	global_store_dword v[4:5], v6, off
.LBB0_773:
	s_or_b64 exec, exec, s[4:5]
	ds_read_b32 v3, v208 offset:72
	s_waitcnt lgkmcnt(0)
	v_rcp_f32_e32 v3, v3
	s_nop 0
	v_mul_f32_e32 v5, v60, v3
	v_mul_f32_e32 v4, v12, v3
	v_mul_f32_e32 v6, v5, v5
	v_mul_f32_e32 v8, v44, v3
	v_fmac_f32_e32 v6, v4, v4
	v_fmac_f32_e32 v6, v8, v8
	v_mul_f32_e32 v9, v28, v3
	v_fmac_f32_e32 v6, v9, v9
	v_cvt_pk_bf16_f32 v4, v4, v4
	s_waitcnt lgkmcnt(0)
	v_add_f32_dpp v3, v6, v6 quad_perm:[1,0,3,2] row_mask:0xf bank_mask:0xf
	s_waitcnt lgkmcnt(0)
	s_nop 1
	v_add_f32_dpp v10, v3, v3 quad_perm:[2,3,0,1] row_mask:0xf bank_mask:0xf
	v_or_b32_e32 v3, 18, v207
	v_lshlrev_b32_e32 v194, 12, v3
	v_lshl_add_u64 v[6:7], v[66:67], 0, v[194:195]
	global_store_short v[6:7], v4, off
	s_waitcnt lgkmcnt(0)
	v_add_f32_dpp v10, v10, v10 row_half_mirror row_mask:0xf bank_mask:0xf
	v_cvt_pk_bf16_f32 v4, v5, v5
	global_store_short v[6:7], v4, off offset:64
	v_cvt_pk_bf16_f32 v8, v8, v8
	global_store_short v[6:7], v8, off offset:128
	s_waitcnt lgkmcnt(0)
	v_add_f32_dpp v4, v10, v10 row_mirror row_mask:0xf bank_mask:0xf
	v_mov_b32_e32 v5, v4
	s_nop 1
	v_permlane16_swap_b32_e32 v4, v5
	v_cvt_pk_bf16_f32 v8, v9, v9
	global_store_short v[6:7], v8, off offset:192
	s_and_saveexec_b64 s[4:5], vcc
	s_cbranch_execz .LBB0_775
	s_waitcnt lgkmcnt(0)
	v_add_f32_e32 v6, v4, v5
	v_or_b32_e32 v4, v3, v196
	v_ashrrev_i32_e32 v5, 31, v4
	v_lshlrev_b64 v[4:5], 6, v[4:5]
	v_lshl_add_u64 v[4:5], s[18:19], 0, v[4:5]
	global_store_dword v[4:5], v6, off
.LBB0_775:
	s_or_b64 exec, exec, s[4:5]
	ds_read_b32 v3, v208 offset:76
	s_waitcnt lgkmcnt(0)
	v_rcp_f32_e32 v3, v3
	s_nop 0
	v_mul_f32_e32 v5, v61, v3
	v_mul_f32_e32 v4, v13, v3
	v_mul_f32_e32 v6, v5, v5
	v_mul_f32_e32 v8, v45, v3
	v_fmac_f32_e32 v6, v4, v4
	v_fmac_f32_e32 v6, v8, v8
	v_mul_f32_e32 v9, v29, v3
	v_fmac_f32_e32 v6, v9, v9
	v_cvt_pk_bf16_f32 v4, v4, v4
	s_waitcnt lgkmcnt(0)
	v_add_f32_dpp v3, v6, v6 quad_perm:[1,0,3,2] row_mask:0xf bank_mask:0xf
	s_waitcnt lgkmcnt(0)
	s_nop 1
	v_add_f32_dpp v10, v3, v3 quad_perm:[2,3,0,1] row_mask:0xf bank_mask:0xf
	v_or_b32_e32 v3, 19, v207
	v_lshlrev_b32_e32 v194, 12, v3
	v_lshl_add_u64 v[6:7], v[66:67], 0, v[194:195]
	global_store_short v[6:7], v4, off
	s_waitcnt lgkmcnt(0)
	v_add_f32_dpp v10, v10, v10 row_half_mirror row_mask:0xf bank_mask:0xf
	v_cvt_pk_bf16_f32 v4, v5, v5
	global_store_short v[6:7], v4, off offset:64
	v_cvt_pk_bf16_f32 v8, v8, v8
	global_store_short v[6:7], v8, off offset:128
	s_waitcnt lgkmcnt(0)
	v_add_f32_dpp v4, v10, v10 row_mirror row_mask:0xf bank_mask:0xf
	v_mov_b32_e32 v5, v4
	s_nop 1
	v_permlane16_swap_b32_e32 v4, v5
	v_cvt_pk_bf16_f32 v8, v9, v9
	global_store_short v[6:7], v8, off offset:192
	s_and_saveexec_b64 s[4:5], vcc
	s_cbranch_execz .LBB0_777
	s_waitcnt lgkmcnt(0)
	v_add_f32_e32 v6, v4, v5
	v_or_b32_e32 v4, v3, v196
	v_ashrrev_i32_e32 v5, 31, v4
	v_lshlrev_b64 v[4:5], 6, v[4:5]
	v_lshl_add_u64 v[4:5], s[18:19], 0, v[4:5]
	global_store_dword v[4:5], v6, off
.LBB0_777:
	s_or_b64 exec, exec, s[4:5]
	ds_read_b32 v3, v208 offset:96
	s_waitcnt lgkmcnt(0)
	v_rcp_f32_e32 v3, v3
	s_nop 0
	v_mul_f32_e32 v5, v62, v3
	v_mul_f32_e32 v4, v14, v3
	v_mul_f32_e32 v6, v5, v5
	v_mul_f32_e32 v8, v46, v3
	v_fmac_f32_e32 v6, v4, v4
	v_fmac_f32_e32 v6, v8, v8
	v_mul_f32_e32 v9, v30, v3
	v_fmac_f32_e32 v6, v9, v9
	v_cvt_pk_bf16_f32 v4, v4, v4
	s_waitcnt lgkmcnt(0)
	v_add_f32_dpp v3, v6, v6 quad_perm:[1,0,3,2] row_mask:0xf bank_mask:0xf
	s_waitcnt lgkmcnt(0)
	s_nop 1
	v_add_f32_dpp v10, v3, v3 quad_perm:[2,3,0,1] row_mask:0xf bank_mask:0xf
	v_or_b32_e32 v3, 24, v207
	v_lshlrev_b32_e32 v194, 12, v3
	v_lshl_add_u64 v[6:7], v[66:67], 0, v[194:195]
	global_store_short v[6:7], v4, off
	s_waitcnt lgkmcnt(0)
	v_add_f32_dpp v10, v10, v10 row_half_mirror row_mask:0xf bank_mask:0xf
	v_cvt_pk_bf16_f32 v4, v5, v5
	global_store_short v[6:7], v4, off offset:64
	v_cvt_pk_bf16_f32 v8, v8, v8
	global_store_short v[6:7], v8, off offset:128
	s_waitcnt lgkmcnt(0)
	v_add_f32_dpp v4, v10, v10 row_mirror row_mask:0xf bank_mask:0xf
	v_mov_b32_e32 v5, v4
	s_nop 1
	v_permlane16_swap_b32_e32 v4, v5
	v_cvt_pk_bf16_f32 v8, v9, v9
	global_store_short v[6:7], v8, off offset:192
	s_and_saveexec_b64 s[4:5], vcc
	s_cbranch_execz .LBB0_779
	s_waitcnt lgkmcnt(0)
	v_add_f32_e32 v6, v4, v5
	v_or_b32_e32 v4, v3, v196
	v_ashrrev_i32_e32 v5, 31, v4
	v_lshlrev_b64 v[4:5], 6, v[4:5]
	v_lshl_add_u64 v[4:5], s[18:19], 0, v[4:5]
	global_store_dword v[4:5], v6, off
.LBB0_779:
	s_or_b64 exec, exec, s[4:5]
	ds_read_b32 v3, v208 offset:100
	s_waitcnt lgkmcnt(0)
	v_rcp_f32_e32 v3, v3
	s_nop 0
	v_mul_f32_e32 v5, v63, v3
	v_mul_f32_e32 v4, v15, v3
	v_mul_f32_e32 v6, v5, v5
	v_mul_f32_e32 v8, v47, v3
	v_fmac_f32_e32 v6, v4, v4
	v_fmac_f32_e32 v6, v8, v8
	v_mul_f32_e32 v9, v31, v3
	v_fmac_f32_e32 v6, v9, v9
	v_cvt_pk_bf16_f32 v4, v4, v4
	s_waitcnt lgkmcnt(0)
	v_add_f32_dpp v3, v6, v6 quad_perm:[1,0,3,2] row_mask:0xf bank_mask:0xf
	s_waitcnt lgkmcnt(0)
	s_nop 1
	v_add_f32_dpp v10, v3, v3 quad_perm:[2,3,0,1] row_mask:0xf bank_mask:0xf
	v_or_b32_e32 v3, 25, v207
	v_lshlrev_b32_e32 v194, 12, v3
	v_lshl_add_u64 v[6:7], v[66:67], 0, v[194:195]
	global_store_short v[6:7], v4, off
	s_waitcnt lgkmcnt(0)
	v_add_f32_dpp v10, v10, v10 row_half_mirror row_mask:0xf bank_mask:0xf
	v_cvt_pk_bf16_f32 v4, v5, v5
	global_store_short v[6:7], v4, off offset:64
	v_cvt_pk_bf16_f32 v8, v8, v8
	global_store_short v[6:7], v8, off offset:128
	s_waitcnt lgkmcnt(0)
	v_add_f32_dpp v4, v10, v10 row_mirror row_mask:0xf bank_mask:0xf
	v_mov_b32_e32 v5, v4
	s_nop 1
	v_permlane16_swap_b32_e32 v4, v5
	v_cvt_pk_bf16_f32 v8, v9, v9
	global_store_short v[6:7], v8, off offset:192
	s_and_saveexec_b64 s[4:5], vcc
	s_cbranch_execz .LBB0_781
	s_waitcnt lgkmcnt(0)
	v_add_f32_e32 v6, v4, v5
	v_or_b32_e32 v4, v3, v196
	v_ashrrev_i32_e32 v5, 31, v4
	v_lshlrev_b64 v[4:5], 6, v[4:5]
	v_lshl_add_u64 v[4:5], s[18:19], 0, v[4:5]
	global_store_dword v[4:5], v6, off
.LBB0_781:
	s_or_b64 exec, exec, s[4:5]
	ds_read_b32 v3, v208 offset:104
	s_waitcnt lgkmcnt(0)
	v_rcp_f32_e32 v3, v3
	s_nop 0
	v_mul_f32_e32 v5, v64, v3
	v_mul_f32_e32 v4, v16, v3
	v_mul_f32_e32 v6, v5, v5
	v_mul_f32_e32 v8, v48, v3
	v_fmac_f32_e32 v6, v4, v4
	v_fmac_f32_e32 v6, v8, v8
	v_mul_f32_e32 v9, v32, v3
	v_fmac_f32_e32 v6, v9, v9
	v_cvt_pk_bf16_f32 v4, v4, v4
	s_waitcnt lgkmcnt(0)
	v_add_f32_dpp v3, v6, v6 quad_perm:[1,0,3,2] row_mask:0xf bank_mask:0xf
	s_waitcnt lgkmcnt(0)
	s_nop 1
	v_add_f32_dpp v10, v3, v3 quad_perm:[2,3,0,1] row_mask:0xf bank_mask:0xf
	v_or_b32_e32 v3, 26, v207
	v_lshlrev_b32_e32 v194, 12, v3
	v_lshl_add_u64 v[6:7], v[66:67], 0, v[194:195]
	global_store_short v[6:7], v4, off
	s_waitcnt lgkmcnt(0)
	v_add_f32_dpp v10, v10, v10 row_half_mirror row_mask:0xf bank_mask:0xf
	v_cvt_pk_bf16_f32 v4, v5, v5
	global_store_short v[6:7], v4, off offset:64
	v_cvt_pk_bf16_f32 v8, v8, v8
	global_store_short v[6:7], v8, off offset:128
	s_waitcnt lgkmcnt(0)
	v_add_f32_dpp v4, v10, v10 row_mirror row_mask:0xf bank_mask:0xf
	v_mov_b32_e32 v5, v4
	s_nop 1
	v_permlane16_swap_b32_e32 v4, v5
	v_cvt_pk_bf16_f32 v8, v9, v9
	global_store_short v[6:7], v8, off offset:192
	s_and_saveexec_b64 s[4:5], vcc
	s_cbranch_execz .LBB0_783
	s_waitcnt lgkmcnt(0)
	v_add_f32_e32 v6, v4, v5
	v_or_b32_e32 v4, v3, v196
	v_ashrrev_i32_e32 v5, 31, v4
	v_lshlrev_b64 v[4:5], 6, v[4:5]
	v_lshl_add_u64 v[4:5], s[18:19], 0, v[4:5]
	global_store_dword v[4:5], v6, off
.LBB0_783:
	s_or_b64 exec, exec, s[4:5]
	ds_read_b32 v3, v208 offset:108
	s_waitcnt lgkmcnt(0)
	v_rcp_f32_e32 v3, v3
	s_nop 0
	v_mul_f32_e32 v5, v65, v3
	v_mul_f32_e32 v4, v17, v3
	v_mul_f32_e32 v6, v5, v5
	v_mul_f32_e32 v8, v49, v3
	v_fmac_f32_e32 v6, v4, v4
	v_fmac_f32_e32 v6, v8, v8
	v_mul_f32_e32 v9, v33, v3
	v_fmac_f32_e32 v6, v9, v9
	v_cvt_pk_bf16_f32 v4, v4, v4
	s_waitcnt lgkmcnt(0)
	v_add_f32_dpp v2, v6, v6 quad_perm:[1,0,3,2] row_mask:0xf bank_mask:0xf
	s_waitcnt lgkmcnt(0)
	s_nop 1
	v_add_f32_dpp v3, v2, v2 quad_perm:[2,3,0,1] row_mask:0xf bank_mask:0xf
	v_or_b32_e32 v2, 27, v207
	v_lshlrev_b32_e32 v194, 12, v2
	v_lshl_add_u64 v[6:7], v[66:67], 0, v[194:195]
	global_store_short v[6:7], v4, off
	s_waitcnt lgkmcnt(0)
	v_add_f32_dpp v3, v3, v3 row_half_mirror row_mask:0xf bank_mask:0xf
	v_cvt_pk_bf16_f32 v4, v5, v5
	global_store_short v[6:7], v4, off offset:64
	v_cvt_pk_bf16_f32 v5, v8, v8
	global_store_short v[6:7], v5, off offset:128
	s_waitcnt lgkmcnt(0)
	v_add_f32_dpp v3, v3, v3 row_mirror row_mask:0xf bank_mask:0xf
	v_mov_b32_e32 v4, v3
	s_nop 1
	v_permlane16_swap_b32_e32 v3, v4
	v_cvt_pk_bf16_f32 v5, v9, v9
	global_store_short v[6:7], v5, off offset:192
	s_and_saveexec_b64 s[4:5], vcc
	s_cbranch_execz .LBB0_728
	v_or_b32_e32 v2, v2, v196
	s_waitcnt lgkmcnt(0)
	v_add_f32_e32 v4, v3, v4
	v_ashrrev_i32_e32 v3, 31, v2
	v_lshlrev_b64 v[2:3], 6, v[2:3]
	v_lshl_add_u64 v[2:3], s[18:19], 0, v[2:3]
	global_store_dword v[2:3], v4, off
	s_branch .LBB0_728

.LBB0_1774:
	v_add_f32_e32 v99, 0, v82
	v_add_f32_e32 v100, 0, v83
	v_mov_b32_e32 v101, v195
	v_mov_b32_e32 v102, v195
	s_nop 0
	v_add_f32_e32 v101, v84, v101
	v_add_f32_e32 v102, v85, v102
	s_nop 0
	v_add_f32_e32 v99, v86, v99
	v_add_f32_e32 v100, v87, v100
	v_cvt_pk_bf16_f32 v82, v82, v83
	v_cvt_pk_bf16_f32 v83, v84, v85
	v_cvt_pk_bf16_f32 v84, v86, v87
	v_cvt_pk_bf16_f32 v85, v88, v89
	s_nop 0
	v_permlane32_swap_b32_e32 v82, v84
	v_permlane32_swap_b32_e32 v83, v85
	v_add_f32_e32 v86, v88, v101
	v_add_f32_e32 v87, v89, v102
	s_nop 0
	v_add_f32_e32 v88, v90, v99
	v_add_f32_e32 v89, v91, v100
	s_nop 0
	v_add_f32_e32 v99, v92, v86
	v_add_f32_e32 v100, v93, v87
	s_nop 0
	v_add_f32_e32 v101, v94, v88
	v_add_f32_e32 v102, v95, v89
	v_cvt_pk_bf16_f32 v86, v90, v91
	v_cvt_pk_bf16_f32 v87, v92, v93
	v_cvt_pk_bf16_f32 v88, v94, v95
	v_cvt_pk_bf16_f32 v89, v96, v97
	s_nop 0
	v_permlane32_swap_b32_e32 v86, v88
	v_permlane32_swap_b32_e32 v87, v89
	v_add_f32_e32 v90, v96, v99
	v_add_f32_e32 v91, v97, v100
	s_nop 0
	v_add_f32_e32 v92, v66, v101
	v_add_f32_e32 v93, v67, v102
	s_nop 0
	v_add_f32_e32 v94, v68, v90
	v_add_f32_e32 v95, v69, v91
	s_nop 0
	v_add_f32_e32 v96, v70, v92
	v_add_f32_e32 v97, v71, v93
	v_cvt_pk_bf16_f32 v90, v66, v67
	v_cvt_pk_bf16_f32 v91, v68, v69
	v_cvt_pk_bf16_f32 v92, v70, v71
	v_cvt_pk_bf16_f32 v93, v72, v73
	s_nop 0
	v_permlane32_swap_b32_e32 v90, v92
	v_permlane32_swap_b32_e32 v91, v93
	v_add_f32_e32 v66, v72, v94
	v_add_f32_e32 v67, v73, v95
	s_nop 0
	v_add_f32_e32 v68, v74, v96
	v_add_f32_e32 v69, v75, v97
	s_nop 0
	v_add_f32_e32 v66, v76, v66
	v_add_f32_e32 v67, v77, v67
	s_nop 0
	v_add_f32_e32 v72, v78, v68
	v_add_f32_e32 v73, v79, v69
	v_cvt_pk_bf16_f32 v68, v74, v75
	v_cvt_pk_bf16_f32 v69, v76, v77
	v_cvt_pk_bf16_f32 v70, v78, v79
	v_cvt_pk_bf16_f32 v71, v80, v81
	s_nop 0
	v_permlane32_swap_b32_e32 v68, v70
	v_permlane32_swap_b32_e32 v69, v71
	v_add_f32_e32 v66, v80, v66
	v_add_f32_e32 v67, v81, v67
	s_nop 0
	v_add_f32_e32 v72, v72, v73
	v_add_f32_e32 v66, v66, v67
	v_add_u32_e32 v99, s8, v211
	v_add_f32_e32 v66, v72, v66
	ds_read_b64_tr_b16 v[72:73], v99
	ds_read_b64_tr_b16 v[74:75], v99 offset:2048
	ds_read_b64_tr_b16 v[76:77], v99 offset:512
	ds_read_b64_tr_b16 v[94:95], v99 offset:1024
	ds_read_b64_tr_b16 v[78:79], v99 offset:2560
	ds_read_b64_tr_b16 v[96:97], v99 offset:3072
	s_waitcnt lgkmcnt(4)
	v_mfma_f32_32x32x16_bf16 v[2:17], v[82:85], v[72:75], v[2:17]
	v_mov_b32_e32 v67, v66
	s_nop 1
	v_permlane32_swap_b32_e32 v66, v67
	s_waitcnt lgkmcnt(1)
	v_mfma_f32_32x32x16_bf16 v[50:65], v[82:85], v[76:79], v[50:65]
	ds_read_b64_tr_b16 v[72:73], v99 offset:1536
	ds_read_b64_tr_b16 v[74:75], v99 offset:3584
	s_waitcnt lgkmcnt(2)
	v_mfma_f32_32x32x16_bf16 v[34:49], v[82:85], v[94:97], v[34:49]
	ds_read_b64_tr_b16 v[76:77], v99 offset:4096
	ds_read_b64_tr_b16 v[78:79], v99 offset:6144
	s_waitcnt lgkmcnt(2)
	v_mfma_f32_32x32x16_bf16 v[18:33], v[82:85], v[72:75], v[18:33]
	ds_read_b64_tr_b16 v[94:95], v99 offset:4608
	ds_read_b64_tr_b16 v[96:97], v99 offset:6656
	s_waitcnt lgkmcnt(2)
	v_mfma_f32_32x32x16_bf16 v[2:17], v[86:89], v[76:79], v[2:17]
	ds_read_b64_tr_b16 v[72:73], v99 offset:5120
	ds_read_b64_tr_b16 v[74:75], v99 offset:7168
	s_waitcnt lgkmcnt(2)
	v_mfma_f32_32x32x16_bf16 v[50:65], v[86:89], v[94:97], v[50:65]
	ds_read_b64_tr_b16 v[76:77], v99 offset:5632
	ds_read_b64_tr_b16 v[78:79], v99 offset:7680
	s_waitcnt lgkmcnt(2)
	v_mfma_f32_32x32x16_bf16 v[34:49], v[86:89], v[72:75], v[34:49]
	ds_read_b64_tr_b16 v[80:81], v99 offset:8192
	ds_read_b64_tr_b16 v[82:83], v99 offset:10240
	s_waitcnt lgkmcnt(2)
	v_mfma_f32_32x32x16_bf16 v[18:33], v[86:89], v[76:79], v[18:33]
	ds_read_b64_tr_b16 v[72:73], v99 offset:8704
	ds_read_b64_tr_b16 v[74:75], v99 offset:10752
	s_waitcnt lgkmcnt(2)
	v_mfma_f32_32x32x16_bf16 v[2:17], v[90:93], v[80:83], v[2:17]
	ds_read_b64_tr_b16 v[76:77], v99 offset:9216
	ds_read_b64_tr_b16 v[78:79], v99 offset:11264
	s_waitcnt lgkmcnt(2)
	v_mfma_f32_32x32x16_bf16 v[50:65], v[90:93], v[72:75], v[50:65]
	ds_read_b64_tr_b16 v[80:81], v99 offset:9728
	ds_read_b64_tr_b16 v[82:83], v99 offset:11776
	s_waitcnt lgkmcnt(2)
	v_mfma_f32_32x32x16_bf16 v[34:49], v[90:93], v[76:79], v[34:49]
	ds_read_b64_tr_b16 v[72:73], v99 offset:12288
	ds_read_b64_tr_b16 v[74:75], v99 offset:14336
	s_waitcnt lgkmcnt(2)
	v_mfma_f32_32x32x16_bf16 v[18:33], v[90:93], v[80:83], v[18:33]
	ds_read_b64_tr_b16 v[76:77], v99 offset:12800
	ds_read_b64_tr_b16 v[78:79], v99 offset:14848
	s_waitcnt lgkmcnt(2)
	v_mfma_f32_32x32x16_bf16 v[2:17], v[68:71], v[72:75], v[2:17]
	ds_read_b64_tr_b16 v[80:81], v99 offset:13312
	ds_read_b64_tr_b16 v[82:83], v99 offset:15360
	s_waitcnt lgkmcnt(2)
	v_mfma_f32_32x32x16_bf16 v[50:65], v[68:71], v[76:79], v[50:65]
	ds_read_b64_tr_b16 v[72:73], v99 offset:13824
	ds_read_b64_tr_b16 v[74:75], v99 offset:15872
	s_waitcnt lgkmcnt(2)
	v_mfma_f32_32x32x16_bf16 v[34:49], v[68:71], v[80:83], v[34:49]
	s_waitcnt lgkmcnt(0)
	v_mfma_f32_32x32x16_bf16 v[18:33], v[68:71], v[72:75], v[18:33]
	v_cmp_gt_u32_e32 vcc, 32, v194
	s_and_saveexec_b64 s[4:5], vcc
	v_add_f32_e32 v68, v130, v131
	v_fmac_f32_e32 v68, v197, v212
	v_add_f32_e32 v66, v66, v67
	v_fmac_f32_e32 v66, v68, v98
	ds_write_b32 v213, v66
	s_or_b64 exec, exec, s[4:5]
	s_waitcnt lgkmcnt(0)
	ds_read_b32 v66, v208
	s_lshl_b32 s4, s42, 12
	s_add_u32 s6, s72, s4
	s_addc_u32 s7, s73, 0
	s_add_u32 s4, s6, s16
	s_waitcnt lgkmcnt(0)
	v_rcp_f32_e32 v66, v66
	s_addc_u32 s5, s7, s17
	s_mul_hi_i32 s8, s42, 0xfffff040
	s_mulk_i32 s42, 0xf040
	v_mul_f32_e32 v68, v2, v66
	v_mul_f32_e32 v69, v50, v66
	v_and_b32_e32 v2, 64, v206
	v_mul_f32_e32 v50, v69, v69
	v_add_u32_e32 v70, 64, v2
	v_xor_b32_e32 v2, 1, v206
	v_fmac_f32_e32 v50, v68, v68
	v_mul_f32_e32 v71, v34, v66
	v_cmp_lt_i32_e32 vcc, v2, v70
	v_fmac_f32_e32 v50, v71, v71
	v_mul_f32_e32 v74, v18, v66
	v_cndmask_b32_e32 v2, v206, v2, vcc
	v_fmac_f32_e32 v50, v74, v74
	v_lshlrev_b32_e32 v2, 2, v2
	s_add_u32 s6, s6, s42
	s_addc_u32 s7, s7, s8
	s_add_u32 s6, s6, s14
	s_addc_u32 s7, s7, s15
	s_waitcnt lgkmcnt(0)
	v_add_f32_dpp v34, v50, v50 quad_perm:[1,0,3,2] row_mask:0xf bank_mask:0xf
	v_xor_b32_e32 v18, 2, v206
	v_cmp_lt_i32_e32 vcc, v18, v70
	v_ashrrev_i32_e32 v197, 31, v196
	s_add_u32 s14, s6, 0xf00020
	v_cndmask_b32_e32 v18, v206, v18, vcc
	v_lshlrev_b32_e32 v18, 2, v18
	v_lshlrev_b64 v[66:67], 12, v[196:197]
	s_addc_u32 s15, s7, 0
	v_lshl_add_u64 v[66:67], s[4:5], 0, v[66:67]
	v_lshlrev_b32_e32 v194, 1, v209
	s_waitcnt lgkmcnt(0)
	v_add_f32_dpp v50, v34, v34 quad_perm:[2,3,0,1] row_mask:0xf bank_mask:0xf
	v_xor_b32_e32 v34, 4, v206
	v_cmp_lt_i32_e32 vcc, v34, v70
	v_lshl_add_u64 v[66:67], v[66:67], 0, v[194:195]
	v_lshl_add_u64 v[66:67], v[66:67], 0, s[12:13]
	v_cndmask_b32_e32 v34, v206, v34, vcc
	v_lshlrev_b32_e32 v34, 2, v34
	v_lshlrev_b32_e32 v194, 14, v210
	v_lshl_add_u64 v[72:73], v[66:67], 0, v[194:195]
	v_cvt_pk_bf16_f32 v68, v68, v68
	global_store_short v[72:73], v68, off
	s_waitcnt lgkmcnt(0)
	v_add_f32_dpp v75, v50, v50 row_half_mirror row_mask:0xf bank_mask:0xf
	v_xor_b32_e32 v50, 8, v206
	v_cmp_lt_i32_e64 s[6:7], v50, v70
	v_cvt_pk_bf16_f32 v68, v69, v69
	global_store_short v[72:73], v68, off offset:64
	v_xor_b32_e32 v68, 16, v206
	v_cndmask_b32_e64 v50, v206, v50, s[6:7]
	v_lshlrev_b32_e32 v50, 2, v50
	v_cmp_lt_i32_e64 s[6:7], v68, v70
	v_cmp_eq_u32_e32 vcc, 0, v209
	v_cvt_pk_bf16_f32 v71, v71, v71
	global_store_short v[72:73], v71, off offset:128
	v_cndmask_b32_e64 v68, v206, v68, s[6:7]
	s_waitcnt lgkmcnt(0)
	v_add_f32_dpp v69, v75, v75 row_mirror row_mask:0xf bank_mask:0xf
	v_lshlrev_b32_e32 v68, 2, v68
	v_mov_b32_e32 v70, v69
	s_nop 1
	v_permlane16_swap_b32_e32 v69, v70
	v_cvt_pk_bf16_f32 v71, v74, v74
	global_store_short v[72:73], v71, off offset:192
	s_and_saveexec_b64 s[4:5], vcc
	s_cbranch_execz .LBB0_1778
	s_waitcnt lgkmcnt(0)
	v_add_f32_e32 v69, v69, v70
	v_or_b32_e32 v70, v207, v196
	v_ashrrev_i32_e32 v71, 31, v70
	v_lshlrev_b64 v[70:71], 6, v[70:71]
	v_lshl_add_u64 v[70:71], s[14:15], 0, v[70:71]
	global_store_dword v[70:71], v69, off
.LBB0_1778:
	s_or_b64 exec, exec, s[4:5]
	ds_read_b32 v69, v208 offset:4
	s_waitcnt lgkmcnt(0)
	v_rcp_f32_e32 v69, v69
	s_nop 0
	v_mul_f32_e32 v51, v51, v69
	v_mul_f32_e32 v72, v3, v69
	v_mul_f32_e32 v3, v51, v51
	v_mul_f32_e32 v73, v35, v69
	v_fmac_f32_e32 v3, v72, v72
	v_fmac_f32_e32 v3, v73, v73
	v_mul_f32_e32 v69, v19, v69
	v_fmac_f32_e32 v3, v69, v69
	v_cvt_pk_bf16_f32 v72, v72, v72
	s_waitcnt lgkmcnt(0)
	v_add_f32_dpp v3, v3, v3 quad_perm:[1,0,3,2] row_mask:0xf bank_mask:0xf
	s_waitcnt lgkmcnt(0)
	s_nop 1
	v_add_f32_dpp v19, v3, v3 quad_perm:[2,3,0,1] row_mask:0xf bank_mask:0xf
	v_or_b32_e32 v3, 1, v207
	v_lshlrev_b32_e32 v194, 12, v3
	v_lshl_add_u64 v[70:71], v[66:67], 0, v[194:195]
	global_store_short v[70:71], v72, off
	s_waitcnt lgkmcnt(0)
	v_add_f32_dpp v19, v19, v19 row_half_mirror row_mask:0xf bank_mask:0xf
	v_cvt_pk_bf16_f32 v51, v51, v51
	global_store_short v[70:71], v51, off offset:64
	v_cvt_pk_bf16_f32 v51, v73, v73
	global_store_short v[70:71], v51, off offset:128
	s_waitcnt lgkmcnt(0)
	v_add_f32_dpp v19, v19, v19 row_mirror row_mask:0xf bank_mask:0xf
	v_mov_b32_e32 v35, v19
	s_nop 1
	v_permlane16_swap_b32_e32 v19, v35
	v_cvt_pk_bf16_f32 v51, v69, v69
	global_store_short v[70:71], v51, off offset:192
	s_and_saveexec_b64 s[4:5], vcc
	s_cbranch_execz .LBB0_1780
	v_or_b32_e32 v70, v3, v196
	v_ashrrev_i32_e32 v71, 31, v70
	v_lshlrev_b64 v[70:71], 6, v[70:71]
	s_waitcnt lgkmcnt(0)
	v_add_f32_e32 v19, v19, v35
	v_lshl_add_u64 v[70:71], s[14:15], 0, v[70:71]
	global_store_dword v[70:71], v19, off
.LBB0_1780:
	s_or_b64 exec, exec, s[4:5]
	ds_read_b32 v3, v208 offset:8
	s_waitcnt lgkmcnt(0)
	v_rcp_f32_e32 v3, v3
	s_nop 0
	v_mul_f32_e32 v19, v52, v3
	v_mul_f32_e32 v4, v4, v3
	v_mul_f32_e32 v35, v36, v3
	v_mul_f32_e32 v36, v19, v19
	v_fmac_f32_e32 v36, v4, v4
	v_fmac_f32_e32 v36, v35, v35
	v_mul_f32_e32 v20, v20, v3
	v_fmac_f32_e32 v36, v20, v20
	v_cvt_pk_bf16_f32 v4, v4, v4
	s_waitcnt lgkmcnt(0)
	v_add_f32_dpp v3, v36, v36 quad_perm:[1,0,3,2] row_mask:0xf bank_mask:0xf
	s_waitcnt lgkmcnt(0)
	s_nop 1
	v_add_f32_dpp v36, v3, v3 quad_perm:[2,3,0,1] row_mask:0xf bank_mask:0xf
	v_or_b32_e32 v3, 2, v207
	v_lshlrev_b32_e32 v194, 12, v3
	v_lshl_add_u64 v[70:71], v[66:67], 0, v[194:195]
	global_store_short v[70:71], v4, off
	s_waitcnt lgkmcnt(0)
	v_add_f32_dpp v36, v36, v36 row_half_mirror row_mask:0xf bank_mask:0xf
	v_cvt_pk_bf16_f32 v4, v19, v19
	global_store_short v[70:71], v4, off offset:64
	v_cvt_pk_bf16_f32 v35, v35, v35
	global_store_short v[70:71], v35, off offset:128
	s_waitcnt lgkmcnt(0)
	v_add_f32_dpp v4, v36, v36 row_mirror row_mask:0xf bank_mask:0xf
	v_mov_b32_e32 v19, v4
	s_nop 1
	v_permlane16_swap_b32_e32 v4, v19
	v_cvt_pk_bf16_f32 v20, v20, v20
	global_store_short v[70:71], v20, off offset:192
	s_and_saveexec_b64 s[4:5], vcc
	s_cbranch_execz .LBB0_1782
	v_or_b32_e32 v70, v3, v196
	v_ashrrev_i32_e32 v71, 31, v70
	v_lshlrev_b64 v[70:71], 6, v[70:71]
	s_waitcnt lgkmcnt(0)
	v_add_f32_e32 v4, v4, v19
	v_lshl_add_u64 v[70:71], s[14:15], 0, v[70:71]
	global_store_dword v[70:71], v4, off
.LBB0_1782:
	s_or_b64 exec, exec, s[4:5]
	ds_read_b32 v3, v208 offset:12
	s_waitcnt lgkmcnt(0)
	v_rcp_f32_e32 v3, v3
	s_nop 0
	v_mul_f32_e32 v4, v5, v3
	v_mul_f32_e32 v5, v53, v3
	v_mul_f32_e32 v20, v5, v5
	v_mul_f32_e32 v19, v37, v3
	v_fmac_f32_e32 v20, v4, v4
	v_fmac_f32_e32 v20, v19, v19
	v_mul_f32_e32 v35, v21, v3
	v_fmac_f32_e32 v20, v35, v35
	v_cvt_pk_bf16_f32 v4, v4, v4
	s_waitcnt lgkmcnt(0)
	v_add_f32_dpp v3, v20, v20 quad_perm:[1,0,3,2] row_mask:0xf bank_mask:0xf
	s_waitcnt lgkmcnt(0)
	s_nop 1
	v_add_f32_dpp v36, v3, v3 quad_perm:[2,3,0,1] row_mask:0xf bank_mask:0xf
	v_or_b32_e32 v3, 3, v207
	v_lshlrev_b32_e32 v194, 12, v3
	v_lshl_add_u64 v[20:21], v[66:67], 0, v[194:195]
	global_store_short v[20:21], v4, off
	s_waitcnt lgkmcnt(0)
	v_add_f32_dpp v36, v36, v36 row_half_mirror row_mask:0xf bank_mask:0xf
	v_cvt_pk_bf16_f32 v4, v5, v5
	global_store_short v[20:21], v4, off offset:64
	v_cvt_pk_bf16_f32 v19, v19, v19
	global_store_short v[20:21], v19, off offset:128
	s_waitcnt lgkmcnt(0)
	v_add_f32_dpp v4, v36, v36 row_mirror row_mask:0xf bank_mask:0xf
	v_mov_b32_e32 v5, v4
	s_nop 1
	v_permlane16_swap_b32_e32 v4, v5
	v_cvt_pk_bf16_f32 v19, v35, v35
	global_store_short v[20:21], v19, off offset:192
	s_and_saveexec_b64 s[4:5], vcc
	s_cbranch_execz .LBB0_1784
	s_waitcnt lgkmcnt(0)
	v_add_f32_e32 v19, v4, v5
	v_or_b32_e32 v4, v3, v196
	v_ashrrev_i32_e32 v5, 31, v4
	v_lshlrev_b64 v[4:5], 6, v[4:5]
	v_lshl_add_u64 v[4:5], s[14:15], 0, v[4:5]
	global_store_dword v[4:5], v19, off
.LBB0_1784:
	s_or_b64 exec, exec, s[4:5]
	ds_read_b32 v3, v208 offset:32
	s_waitcnt lgkmcnt(0)
	v_rcp_f32_e32 v3, v3
	s_nop 0
	v_mul_f32_e32 v5, v54, v3
	v_mul_f32_e32 v4, v6, v3
	v_mul_f32_e32 v19, v5, v5
	v_mul_f32_e32 v6, v38, v3
	v_fmac_f32_e32 v19, v4, v4
	v_fmac_f32_e32 v19, v6, v6
	v_mul_f32_e32 v22, v22, v3
	v_fmac_f32_e32 v19, v22, v22
	v_cvt_pk_bf16_f32 v4, v4, v4
	s_waitcnt lgkmcnt(0)
	v_add_f32_dpp v3, v19, v19 quad_perm:[1,0,3,2] row_mask:0xf bank_mask:0xf
	s_waitcnt lgkmcnt(0)
	s_nop 1
	v_add_f32_dpp v19, v3, v3 quad_perm:[2,3,0,1] row_mask:0xf bank_mask:0xf
	v_or_b32_e32 v3, 8, v207
	v_lshlrev_b32_e32 v194, 12, v3
	v_lshl_add_u64 v[20:21], v[66:67], 0, v[194:195]
	global_store_short v[20:21], v4, off
	s_waitcnt lgkmcnt(0)
	v_add_f32_dpp v19, v19, v19 row_half_mirror row_mask:0xf bank_mask:0xf
	v_cvt_pk_bf16_f32 v4, v5, v5
	global_store_short v[20:21], v4, off offset:64
	v_cvt_pk_bf16_f32 v6, v6, v6
	global_store_short v[20:21], v6, off offset:128
	s_waitcnt lgkmcnt(0)
	v_add_f32_dpp v4, v19, v19 row_mirror row_mask:0xf bank_mask:0xf
	v_mov_b32_e32 v5, v4
	s_nop 1
	v_permlane16_swap_b32_e32 v4, v5
	v_cvt_pk_bf16_f32 v6, v22, v22
	global_store_short v[20:21], v6, off offset:192
	s_and_saveexec_b64 s[4:5], vcc
	s_cbranch_execz .LBB0_1786
	s_waitcnt lgkmcnt(0)
	v_add_f32_e32 v6, v4, v5
	v_or_b32_e32 v4, v3, v196
	v_ashrrev_i32_e32 v5, 31, v4
	v_lshlrev_b64 v[4:5], 6, v[4:5]
	v_lshl_add_u64 v[4:5], s[14:15], 0, v[4:5]
	global_store_dword v[4:5], v6, off
.LBB0_1786:
	s_or_b64 exec, exec, s[4:5]
	ds_read_b32 v3, v208 offset:36
	s_waitcnt lgkmcnt(0)
	v_rcp_f32_e32 v3, v3
	s_nop 0
	v_mul_f32_e32 v5, v55, v3
	v_mul_f32_e32 v4, v7, v3
	v_mul_f32_e32 v6, v5, v5
	v_mul_f32_e32 v19, v39, v3
	v_fmac_f32_e32 v6, v4, v4
	v_fmac_f32_e32 v6, v19, v19
	v_mul_f32_e32 v20, v23, v3
	v_fmac_f32_e32 v6, v20, v20
	v_cvt_pk_bf16_f32 v4, v4, v4
	s_waitcnt lgkmcnt(0)
	v_add_f32_dpp v3, v6, v6 quad_perm:[1,0,3,2] row_mask:0xf bank_mask:0xf
	s_waitcnt lgkmcnt(0)
	s_nop 1
	v_add_f32_dpp v21, v3, v3 quad_perm:[2,3,0,1] row_mask:0xf bank_mask:0xf
	v_or_b32_e32 v3, 9, v207
	v_lshlrev_b32_e32 v194, 12, v3
	v_lshl_add_u64 v[6:7], v[66:67], 0, v[194:195]
	global_store_short v[6:7], v4, off
	s_waitcnt lgkmcnt(0)
	v_add_f32_dpp v21, v21, v21 row_half_mirror row_mask:0xf bank_mask:0xf
	v_cvt_pk_bf16_f32 v4, v5, v5
	global_store_short v[6:7], v4, off offset:64
	v_cvt_pk_bf16_f32 v19, v19, v19
	global_store_short v[6:7], v19, off offset:128
	s_waitcnt lgkmcnt(0)
	v_add_f32_dpp v4, v21, v21 row_mirror row_mask:0xf bank_mask:0xf
	v_mov_b32_e32 v5, v4
	s_nop 1
	v_permlane16_swap_b32_e32 v4, v5
	v_cvt_pk_bf16_f32 v19, v20, v20
	global_store_short v[6:7], v19, off offset:192
	s_and_saveexec_b64 s[4:5], vcc
	s_cbranch_execz .LBB0_1788
	s_waitcnt lgkmcnt(0)
	v_add_f32_e32 v6, v4, v5
	v_or_b32_e32 v4, v3, v196
	v_ashrrev_i32_e32 v5, 31, v4
	v_lshlrev_b64 v[4:5], 6, v[4:5]
	v_lshl_add_u64 v[4:5], s[14:15], 0, v[4:5]
	global_store_dword v[4:5], v6, off
.LBB0_1788:
	s_or_b64 exec, exec, s[4:5]
	ds_read_b32 v3, v208 offset:40
	s_waitcnt lgkmcnt(0)
	v_rcp_f32_e32 v3, v3
	s_nop 0
	v_mul_f32_e32 v5, v56, v3
	v_mul_f32_e32 v4, v8, v3
	v_mul_f32_e32 v6, v5, v5
	v_mul_f32_e32 v8, v40, v3
	v_fmac_f32_e32 v6, v4, v4
	v_fmac_f32_e32 v6, v8, v8
	v_mul_f32_e32 v19, v24, v3
	v_fmac_f32_e32 v6, v19, v19
	v_cvt_pk_bf16_f32 v4, v4, v4
	s_waitcnt lgkmcnt(0)
	v_add_f32_dpp v3, v6, v6 quad_perm:[1,0,3,2] row_mask:0xf bank_mask:0xf
	s_waitcnt lgkmcnt(0)
	s_nop 1
	v_add_f32_dpp v20, v3, v3 quad_perm:[2,3,0,1] row_mask:0xf bank_mask:0xf
	v_or_b32_e32 v3, 10, v207
	v_lshlrev_b32_e32 v194, 12, v3
	v_lshl_add_u64 v[6:7], v[66:67], 0, v[194:195]
	global_store_short v[6:7], v4, off
	s_waitcnt lgkmcnt(0)
	v_add_f32_dpp v20, v20, v20 row_half_mirror row_mask:0xf bank_mask:0xf
	v_cvt_pk_bf16_f32 v4, v5, v5
	global_store_short v[6:7], v4, off offset:64
	v_cvt_pk_bf16_f32 v8, v8, v8
	global_store_short v[6:7], v8, off offset:128
	s_waitcnt lgkmcnt(0)
	v_add_f32_dpp v4, v20, v20 row_mirror row_mask:0xf bank_mask:0xf
	v_mov_b32_e32 v5, v4
	s_nop 1
	v_permlane16_swap_b32_e32 v4, v5
	v_cvt_pk_bf16_f32 v8, v19, v19
	global_store_short v[6:7], v8, off offset:192
	s_and_saveexec_b64 s[4:5], vcc
	s_cbranch_execz .LBB0_1790
	s_waitcnt lgkmcnt(0)
	v_add_f32_e32 v6, v4, v5
	v_or_b32_e32 v4, v3, v196
	v_ashrrev_i32_e32 v5, 31, v4
	v_lshlrev_b64 v[4:5], 6, v[4:5]
	v_lshl_add_u64 v[4:5], s[14:15], 0, v[4:5]
	global_store_dword v[4:5], v6, off
.LBB0_1790:
	s_or_b64 exec, exec, s[4:5]
	ds_read_b32 v3, v208 offset:44
	s_waitcnt lgkmcnt(0)
	v_rcp_f32_e32 v3, v3
	s_nop 0
	v_mul_f32_e32 v5, v57, v3
	v_mul_f32_e32 v4, v9, v3
	v_mul_f32_e32 v6, v5, v5
	v_mul_f32_e32 v8, v41, v3
	v_fmac_f32_e32 v6, v4, v4
	v_fmac_f32_e32 v6, v8, v8
	v_mul_f32_e32 v9, v25, v3
	v_fmac_f32_e32 v6, v9, v9
	v_cvt_pk_bf16_f32 v4, v4, v4
	s_waitcnt lgkmcnt(0)
	v_add_f32_dpp v3, v6, v6 quad_perm:[1,0,3,2] row_mask:0xf bank_mask:0xf
	s_waitcnt lgkmcnt(0)
	s_nop 1
	v_add_f32_dpp v19, v3, v3 quad_perm:[2,3,0,1] row_mask:0xf bank_mask:0xf
	v_or_b32_e32 v3, 11, v207
	v_lshlrev_b32_e32 v194, 12, v3
	v_lshl_add_u64 v[6:7], v[66:67], 0, v[194:195]
	global_store_short v[6:7], v4, off
	s_waitcnt lgkmcnt(0)
	v_add_f32_dpp v19, v19, v19 row_half_mirror row_mask:0xf bank_mask:0xf
	v_cvt_pk_bf16_f32 v4, v5, v5
	global_store_short v[6:7], v4, off offset:64
	v_cvt_pk_bf16_f32 v8, v8, v8
	global_store_short v[6:7], v8, off offset:128
	s_waitcnt lgkmcnt(0)
	v_add_f32_dpp v4, v19, v19 row_mirror row_mask:0xf bank_mask:0xf
	v_mov_b32_e32 v5, v4
	s_nop 1
	v_permlane16_swap_b32_e32 v4, v5
	v_cvt_pk_bf16_f32 v8, v9, v9
	global_store_short v[6:7], v8, off offset:192
	s_and_saveexec_b64 s[4:5], vcc
	s_cbranch_execz .LBB0_1792
	s_waitcnt lgkmcnt(0)
	v_add_f32_e32 v6, v4, v5
	v_or_b32_e32 v4, v3, v196
	v_ashrrev_i32_e32 v5, 31, v4
	v_lshlrev_b64 v[4:5], 6, v[4:5]
	v_lshl_add_u64 v[4:5], s[14:15], 0, v[4:5]
	global_store_dword v[4:5], v6, off
.LBB0_1792:
	s_or_b64 exec, exec, s[4:5]
	ds_read_b32 v3, v208 offset:64
	s_waitcnt lgkmcnt(0)
	v_rcp_f32_e32 v3, v3
	s_nop 0
	v_mul_f32_e32 v5, v58, v3
	v_mul_f32_e32 v4, v10, v3
	v_mul_f32_e32 v6, v5, v5
	v_mul_f32_e32 v8, v42, v3
	v_fmac_f32_e32 v6, v4, v4
	v_fmac_f32_e32 v6, v8, v8
	v_mul_f32_e32 v9, v26, v3
	v_fmac_f32_e32 v6, v9, v9
	v_cvt_pk_bf16_f32 v4, v4, v4
	s_waitcnt lgkmcnt(0)
	v_add_f32_dpp v3, v6, v6 quad_perm:[1,0,3,2] row_mask:0xf bank_mask:0xf
	s_waitcnt lgkmcnt(0)
	s_nop 1
	v_add_f32_dpp v10, v3, v3 quad_perm:[2,3,0,1] row_mask:0xf bank_mask:0xf
	v_or_b32_e32 v3, 16, v207
	v_lshlrev_b32_e32 v194, 12, v3
	v_lshl_add_u64 v[6:7], v[66:67], 0, v[194:195]
	global_store_short v[6:7], v4, off
	s_waitcnt lgkmcnt(0)
	v_add_f32_dpp v10, v10, v10 row_half_mirror row_mask:0xf bank_mask:0xf
	v_cvt_pk_bf16_f32 v4, v5, v5
	global_store_short v[6:7], v4, off offset:64
	v_cvt_pk_bf16_f32 v8, v8, v8
	global_store_short v[6:7], v8, off offset:128
	s_waitcnt lgkmcnt(0)
	v_add_f32_dpp v4, v10, v10 row_mirror row_mask:0xf bank_mask:0xf
	v_mov_b32_e32 v5, v4
	s_nop 1
	v_permlane16_swap_b32_e32 v4, v5
	v_cvt_pk_bf16_f32 v8, v9, v9
	global_store_short v[6:7], v8, off offset:192
	s_and_saveexec_b64 s[4:5], vcc
	s_cbranch_execz .LBB0_1794
	s_waitcnt lgkmcnt(0)
	v_add_f32_e32 v6, v4, v5
	v_or_b32_e32 v4, v3, v196
	v_ashrrev_i32_e32 v5, 31, v4
	v_lshlrev_b64 v[4:5], 6, v[4:5]
	v_lshl_add_u64 v[4:5], s[14:15], 0, v[4:5]
	global_store_dword v[4:5], v6, off
.LBB0_1794:
	s_or_b64 exec, exec, s[4:5]
	ds_read_b32 v3, v208 offset:68
	s_waitcnt lgkmcnt(0)
	v_rcp_f32_e32 v3, v3
	s_nop 0
	v_mul_f32_e32 v5, v59, v3
	v_mul_f32_e32 v4, v11, v3
	v_mul_f32_e32 v6, v5, v5
	v_mul_f32_e32 v8, v43, v3
	v_fmac_f32_e32 v6, v4, v4
	v_fmac_f32_e32 v6, v8, v8
	v_mul_f32_e32 v9, v27, v3
	v_fmac_f32_e32 v6, v9, v9
	v_cvt_pk_bf16_f32 v4, v4, v4
	s_waitcnt lgkmcnt(0)
	v_add_f32_dpp v3, v6, v6 quad_perm:[1,0,3,2] row_mask:0xf bank_mask:0xf
	s_waitcnt lgkmcnt(0)
	s_nop 1
	v_add_f32_dpp v10, v3, v3 quad_perm:[2,3,0,1] row_mask:0xf bank_mask:0xf
	v_or_b32_e32 v3, 17, v207
	v_lshlrev_b32_e32 v194, 12, v3
	v_lshl_add_u64 v[6:7], v[66:67], 0, v[194:195]
	global_store_short v[6:7], v4, off
	s_waitcnt lgkmcnt(0)
	v_add_f32_dpp v10, v10, v10 row_half_mirror row_mask:0xf bank_mask:0xf
	v_cvt_pk_bf16_f32 v4, v5, v5
	global_store_short v[6:7], v4, off offset:64
	v_cvt_pk_bf16_f32 v8, v8, v8
	global_store_short v[6:7], v8, off offset:128
	s_waitcnt lgkmcnt(0)
	v_add_f32_dpp v4, v10, v10 row_mirror row_mask:0xf bank_mask:0xf
	v_mov_b32_e32 v5, v4
	s_nop 1
	v_permlane16_swap_b32_e32 v4, v5
	v_cvt_pk_bf16_f32 v8, v9, v9
	global_store_short v[6:7], v8, off offset:192
	s_and_saveexec_b64 s[4:5], vcc
	s_cbranch_execz .LBB0_1796
	s_waitcnt lgkmcnt(0)
	v_add_f32_e32 v6, v4, v5
	v_or_b32_e32 v4, v3, v196
	v_ashrrev_i32_e32 v5, 31, v4
	v_lshlrev_b64 v[4:5], 6, v[4:5]
	v_lshl_add_u64 v[4:5], s[14:15], 0, v[4:5]
	global_store_dword v[4:5], v6, off
.LBB0_1796:
	s_or_b64 exec, exec, s[4:5]
	ds_read_b32 v3, v208 offset:72
	s_waitcnt lgkmcnt(0)
	v_rcp_f32_e32 v3, v3
	s_nop 0
	v_mul_f32_e32 v5, v60, v3
	v_mul_f32_e32 v4, v12, v3
	v_mul_f32_e32 v6, v5, v5
	v_mul_f32_e32 v8, v44, v3
	v_fmac_f32_e32 v6, v4, v4
	v_fmac_f32_e32 v6, v8, v8
	v_mul_f32_e32 v9, v28, v3
	v_fmac_f32_e32 v6, v9, v9
	v_cvt_pk_bf16_f32 v4, v4, v4
	s_waitcnt lgkmcnt(0)
	v_add_f32_dpp v3, v6, v6 quad_perm:[1,0,3,2] row_mask:0xf bank_mask:0xf
	s_waitcnt lgkmcnt(0)
	s_nop 1
	v_add_f32_dpp v10, v3, v3 quad_perm:[2,3,0,1] row_mask:0xf bank_mask:0xf
	v_or_b32_e32 v3, 18, v207
	v_lshlrev_b32_e32 v194, 12, v3
	v_lshl_add_u64 v[6:7], v[66:67], 0, v[194:195]
	global_store_short v[6:7], v4, off
	s_waitcnt lgkmcnt(0)
	v_add_f32_dpp v10, v10, v10 row_half_mirror row_mask:0xf bank_mask:0xf
	v_cvt_pk_bf16_f32 v4, v5, v5
	global_store_short v[6:7], v4, off offset:64
	v_cvt_pk_bf16_f32 v8, v8, v8
	global_store_short v[6:7], v8, off offset:128
	s_waitcnt lgkmcnt(0)
	v_add_f32_dpp v4, v10, v10 row_mirror row_mask:0xf bank_mask:0xf
	v_mov_b32_e32 v5, v4
	s_nop 1
	v_permlane16_swap_b32_e32 v4, v5
	v_cvt_pk_bf16_f32 v8, v9, v9
	global_store_short v[6:7], v8, off offset:192
	s_and_saveexec_b64 s[4:5], vcc
	s_cbranch_execz .LBB0_1798
	s_waitcnt lgkmcnt(0)
	v_add_f32_e32 v6, v4, v5
	v_or_b32_e32 v4, v3, v196
	v_ashrrev_i32_e32 v5, 31, v4
	v_lshlrev_b64 v[4:5], 6, v[4:5]
	v_lshl_add_u64 v[4:5], s[14:15], 0, v[4:5]
	global_store_dword v[4:5], v6, off
.LBB0_1798:
	s_or_b64 exec, exec, s[4:5]
	ds_read_b32 v3, v208 offset:76
	s_waitcnt lgkmcnt(0)
	v_rcp_f32_e32 v3, v3
	s_nop 0
	v_mul_f32_e32 v5, v61, v3
	v_mul_f32_e32 v4, v13, v3
	v_mul_f32_e32 v6, v5, v5
	v_mul_f32_e32 v8, v45, v3
	v_fmac_f32_e32 v6, v4, v4
	v_fmac_f32_e32 v6, v8, v8
	v_mul_f32_e32 v9, v29, v3
	v_fmac_f32_e32 v6, v9, v9
	v_cvt_pk_bf16_f32 v4, v4, v4
	s_waitcnt lgkmcnt(0)
	v_add_f32_dpp v3, v6, v6 quad_perm:[1,0,3,2] row_mask:0xf bank_mask:0xf
	s_waitcnt lgkmcnt(0)
	s_nop 1
	v_add_f32_dpp v10, v3, v3 quad_perm:[2,3,0,1] row_mask:0xf bank_mask:0xf
	v_or_b32_e32 v3, 19, v207
	v_lshlrev_b32_e32 v194, 12, v3
	v_lshl_add_u64 v[6:7], v[66:67], 0, v[194:195]
	global_store_short v[6:7], v4, off
	s_waitcnt lgkmcnt(0)
	v_add_f32_dpp v10, v10, v10 row_half_mirror row_mask:0xf bank_mask:0xf
	v_cvt_pk_bf16_f32 v4, v5, v5
	global_store_short v[6:7], v4, off offset:64
	v_cvt_pk_bf16_f32 v8, v8, v8
	global_store_short v[6:7], v8, off offset:128
	s_waitcnt lgkmcnt(0)
	v_add_f32_dpp v4, v10, v10 row_mirror row_mask:0xf bank_mask:0xf
	v_mov_b32_e32 v5, v4
	s_nop 1
	v_permlane16_swap_b32_e32 v4, v5
	v_cvt_pk_bf16_f32 v8, v9, v9
	global_store_short v[6:7], v8, off offset:192
	s_and_saveexec_b64 s[4:5], vcc
	s_cbranch_execz .LBB0_1800
	s_waitcnt lgkmcnt(0)
	v_add_f32_e32 v6, v4, v5
	v_or_b32_e32 v4, v3, v196
	v_ashrrev_i32_e32 v5, 31, v4
	v_lshlrev_b64 v[4:5], 6, v[4:5]
	v_lshl_add_u64 v[4:5], s[14:15], 0, v[4:5]
	global_store_dword v[4:5], v6, off
.LBB0_1800:
	s_or_b64 exec, exec, s[4:5]
	ds_read_b32 v3, v208 offset:96
	s_waitcnt lgkmcnt(0)
	v_rcp_f32_e32 v3, v3
	s_nop 0
	v_mul_f32_e32 v5, v62, v3
	v_mul_f32_e32 v4, v14, v3
	v_mul_f32_e32 v6, v5, v5
	v_mul_f32_e32 v8, v46, v3
	v_fmac_f32_e32 v6, v4, v4
	v_fmac_f32_e32 v6, v8, v8
	v_mul_f32_e32 v9, v30, v3
	v_fmac_f32_e32 v6, v9, v9
	v_cvt_pk_bf16_f32 v4, v4, v4
	s_waitcnt lgkmcnt(0)
	v_add_f32_dpp v3, v6, v6 quad_perm:[1,0,3,2] row_mask:0xf bank_mask:0xf
	s_waitcnt lgkmcnt(0)
	s_nop 1
	v_add_f32_dpp v10, v3, v3 quad_perm:[2,3,0,1] row_mask:0xf bank_mask:0xf
	v_or_b32_e32 v3, 24, v207
	v_lshlrev_b32_e32 v194, 12, v3
	v_lshl_add_u64 v[6:7], v[66:67], 0, v[194:195]
	global_store_short v[6:7], v4, off
	s_waitcnt lgkmcnt(0)
	v_add_f32_dpp v10, v10, v10 row_half_mirror row_mask:0xf bank_mask:0xf
	v_cvt_pk_bf16_f32 v4, v5, v5
	global_store_short v[6:7], v4, off offset:64
	v_cvt_pk_bf16_f32 v8, v8, v8
	global_store_short v[6:7], v8, off offset:128
	s_waitcnt lgkmcnt(0)
	v_add_f32_dpp v4, v10, v10 row_mirror row_mask:0xf bank_mask:0xf
	v_mov_b32_e32 v5, v4
	s_nop 1
	v_permlane16_swap_b32_e32 v4, v5
	v_cvt_pk_bf16_f32 v8, v9, v9
	global_store_short v[6:7], v8, off offset:192
	s_and_saveexec_b64 s[4:5], vcc
	s_cbranch_execz .LBB0_1802
	s_waitcnt lgkmcnt(0)
	v_add_f32_e32 v6, v4, v5
	v_or_b32_e32 v4, v3, v196
	v_ashrrev_i32_e32 v5, 31, v4
	v_lshlrev_b64 v[4:5], 6, v[4:5]
	v_lshl_add_u64 v[4:5], s[14:15], 0, v[4:5]
	global_store_dword v[4:5], v6, off
.LBB0_1802:
	s_or_b64 exec, exec, s[4:5]
	ds_read_b32 v3, v208 offset:100
	s_waitcnt lgkmcnt(0)
	v_rcp_f32_e32 v3, v3
	s_nop 0
	v_mul_f32_e32 v5, v63, v3
	v_mul_f32_e32 v4, v15, v3
	v_mul_f32_e32 v6, v5, v5
	v_mul_f32_e32 v8, v47, v3
	v_fmac_f32_e32 v6, v4, v4
	v_fmac_f32_e32 v6, v8, v8
	v_mul_f32_e32 v9, v31, v3
	v_fmac_f32_e32 v6, v9, v9
	v_cvt_pk_bf16_f32 v4, v4, v4
	s_waitcnt lgkmcnt(0)
	v_add_f32_dpp v3, v6, v6 quad_perm:[1,0,3,2] row_mask:0xf bank_mask:0xf
	s_waitcnt lgkmcnt(0)
	s_nop 1
	v_add_f32_dpp v10, v3, v3 quad_perm:[2,3,0,1] row_mask:0xf bank_mask:0xf
	v_or_b32_e32 v3, 25, v207
	v_lshlrev_b32_e32 v194, 12, v3
	v_lshl_add_u64 v[6:7], v[66:67], 0, v[194:195]
	global_store_short v[6:7], v4, off
	s_waitcnt lgkmcnt(0)
	v_add_f32_dpp v10, v10, v10 row_half_mirror row_mask:0xf bank_mask:0xf
	v_cvt_pk_bf16_f32 v4, v5, v5
	global_store_short v[6:7], v4, off offset:64
	v_cvt_pk_bf16_f32 v8, v8, v8
	global_store_short v[6:7], v8, off offset:128
	s_waitcnt lgkmcnt(0)
	v_add_f32_dpp v4, v10, v10 row_mirror row_mask:0xf bank_mask:0xf
	v_mov_b32_e32 v5, v4
	s_nop 1
	v_permlane16_swap_b32_e32 v4, v5
	v_cvt_pk_bf16_f32 v8, v9, v9
	global_store_short v[6:7], v8, off offset:192
	s_and_saveexec_b64 s[4:5], vcc
	s_cbranch_execz .LBB0_1804
	s_waitcnt lgkmcnt(0)
	v_add_f32_e32 v6, v4, v5
	v_or_b32_e32 v4, v3, v196
	v_ashrrev_i32_e32 v5, 31, v4
	v_lshlrev_b64 v[4:5], 6, v[4:5]
	v_lshl_add_u64 v[4:5], s[14:15], 0, v[4:5]
	global_store_dword v[4:5], v6, off
.LBB0_1804:
	s_or_b64 exec, exec, s[4:5]
	ds_read_b32 v3, v208 offset:104
	s_waitcnt lgkmcnt(0)
	v_rcp_f32_e32 v3, v3
	s_nop 0
	v_mul_f32_e32 v5, v64, v3
	v_mul_f32_e32 v4, v16, v3
	v_mul_f32_e32 v6, v5, v5
	v_mul_f32_e32 v8, v48, v3
	v_fmac_f32_e32 v6, v4, v4
	v_fmac_f32_e32 v6, v8, v8
	v_mul_f32_e32 v9, v32, v3
	v_fmac_f32_e32 v6, v9, v9
	v_cvt_pk_bf16_f32 v4, v4, v4
	s_waitcnt lgkmcnt(0)
	v_add_f32_dpp v3, v6, v6 quad_perm:[1,0,3,2] row_mask:0xf bank_mask:0xf
	s_waitcnt lgkmcnt(0)
	s_nop 1
	v_add_f32_dpp v10, v3, v3 quad_perm:[2,3,0,1] row_mask:0xf bank_mask:0xf
	v_or_b32_e32 v3, 26, v207
	v_lshlrev_b32_e32 v194, 12, v3
	v_lshl_add_u64 v[6:7], v[66:67], 0, v[194:195]
	global_store_short v[6:7], v4, off
	s_waitcnt lgkmcnt(0)
	v_add_f32_dpp v10, v10, v10 row_half_mirror row_mask:0xf bank_mask:0xf
	v_cvt_pk_bf16_f32 v4, v5, v5
	global_store_short v[6:7], v4, off offset:64
	v_cvt_pk_bf16_f32 v8, v8, v8
	global_store_short v[6:7], v8, off offset:128
	s_waitcnt lgkmcnt(0)
	v_add_f32_dpp v4, v10, v10 row_mirror row_mask:0xf bank_mask:0xf
	v_mov_b32_e32 v5, v4
	s_nop 1
	v_permlane16_swap_b32_e32 v4, v5
	v_cvt_pk_bf16_f32 v8, v9, v9
	global_store_short v[6:7], v8, off offset:192
	s_and_saveexec_b64 s[4:5], vcc
	s_cbranch_execz .LBB0_1806
	s_waitcnt lgkmcnt(0)
	v_add_f32_e32 v6, v4, v5
	v_or_b32_e32 v4, v3, v196
	v_ashrrev_i32_e32 v5, 31, v4
	v_lshlrev_b64 v[4:5], 6, v[4:5]
	v_lshl_add_u64 v[4:5], s[14:15], 0, v[4:5]
	global_store_dword v[4:5], v6, off
.LBB0_1806:
	s_or_b64 exec, exec, s[4:5]
	ds_read_b32 v3, v208 offset:108
	s_waitcnt lgkmcnt(0)
	v_rcp_f32_e32 v3, v3
	s_nop 0
	v_mul_f32_e32 v5, v65, v3
	v_mul_f32_e32 v4, v17, v3
	v_mul_f32_e32 v6, v5, v5
	v_mul_f32_e32 v8, v49, v3
	v_fmac_f32_e32 v6, v4, v4
	v_fmac_f32_e32 v6, v8, v8
	v_mul_f32_e32 v9, v33, v3
	v_fmac_f32_e32 v6, v9, v9
	v_cvt_pk_bf16_f32 v4, v4, v4
	s_waitcnt lgkmcnt(0)
	v_add_f32_dpp v2, v6, v6 quad_perm:[1,0,3,2] row_mask:0xf bank_mask:0xf
	s_waitcnt lgkmcnt(0)
	s_nop 1
	v_add_f32_dpp v3, v2, v2 quad_perm:[2,3,0,1] row_mask:0xf bank_mask:0xf
	v_or_b32_e32 v2, 27, v207
	v_lshlrev_b32_e32 v194, 12, v2
	v_lshl_add_u64 v[6:7], v[66:67], 0, v[194:195]
	global_store_short v[6:7], v4, off
	s_waitcnt lgkmcnt(0)
	v_add_f32_dpp v3, v3, v3 row_half_mirror row_mask:0xf bank_mask:0xf
	v_cvt_pk_bf16_f32 v4, v5, v5
	global_store_short v[6:7], v4, off offset:64
	v_cvt_pk_bf16_f32 v5, v8, v8
	global_store_short v[6:7], v5, off offset:128
	s_waitcnt lgkmcnt(0)
	v_add_f32_dpp v3, v3, v3 row_mirror row_mask:0xf bank_mask:0xf
	v_mov_b32_e32 v4, v3
	s_nop 1
	v_permlane16_swap_b32_e32 v3, v4
	v_cvt_pk_bf16_f32 v5, v9, v9
	global_store_short v[6:7], v5, off offset:192
	s_and_saveexec_b64 s[4:5], vcc
	s_cbranch_execz .LBB0_1751
	v_or_b32_e32 v2, v2, v196
	s_waitcnt lgkmcnt(0)
	v_add_f32_e32 v4, v3, v4
	v_ashrrev_i32_e32 v3, 31, v2
	v_lshlrev_b64 v[2:3], 6, v[2:3]
	v_lshl_add_u64 v[2:3], s[14:15], 0, v[2:3]
	global_store_dword v[2:3], v4, off
	s_branch .LBB0_1751
